# k-loop loop-edge edit: a2/b2 next-tile bases computed branch-free under phase-1 MFMAs, a1 base after the LDS reads, a3/b3 under phase-3 MFMAs, cheap merge pre-test at loop top
# speedup vs baseline: 1.0351x; 1.0052x over previous
; #define PG8_STAGE(bufoff, gbase, voff) do { _Pragma("unroll") for (int _i = 0; _i < 2; ++_i) \
;         __builtin_amdgcn_global_load_lds((const unsigned*)((const char*)(gbase) + (voff)[_i]), (LAS unsigned*)(lds + (bufoff) + ldsw + _i * 8192), 16, 0, 0); } while (0)
; #define PG8_LDA(dst, b, h) do { _Pragma("unroll") for (int m = 0; m < 4; ++m) _Pragma("unroll") for (int k = 0; k < 2; ++k) dst[m][k] = *(const LAS bf16x8*)(lds + PG8_SA(b, h) + aoff + m * 2048 + k * 1024); } while (0)
; #define PG8_LDB(dst, b, h) do { _Pragma("unroll") for (int n = 0; n < 2; ++n) _Pragma("unroll") for (int k = 0; k < 2; ++k) dst[n][k] = *(const LAS bf16x8*)(lds + PG8_SB(b, h) + boff + n * 2048 + k * 1024); } while (0)
; #define PG8_WAIT_V(n) asm volatile("s_waitcnt vmcnt(" #n ")" ::: "memory")
; #define PG8_WAIT_L(n) asm volatile("s_waitcnt lgkmcnt(" #n ")" ::: "memory")
; #define PG8_BAR __builtin_amdgcn_s_barrier()
; #define PG8_SCHED __builtin_amdgcn_sched_barrier(0)
; DI void gemm_phase(LAS unsigned char* lds, int ph, unsigned char* ws, unsigned char* wg, int l, const float* pscale, int G, int cidx, int nx) {
;     ...
;         const bool has_next = S.next(ui + 1, nxt);
;         const char* nA = cA; const char* nB = cB; if (has_next) { PG8_RECFG(); nA = PG8_ABASE(nxt); nB = PG8_BBASE(nxt); }
;         for (int t = 0; t < nt; t += 2) {
;             const bool last = (t == nt - 2);
;             const char* a1 = PG8_KA(t + 1);
;             const char* a2 = last ? nA : PG8_KA(t + 2); const char* b2 = last ? nB : PG8_KB(t + 2);
;             const char* a3 = a2 + kstep; const char* b3 = b2 + kstep;
;             if (zAb != 0 && t != 0 && (t & ntzm) == 0) { unsigned char* wsx = ws; asm volatile("" : "+s"(wsx)); int frx = fr; asm volatile("" : "+v"(frx)); merge_carry(acc, wsx, cur, (t >> lz) - 1, wr, wc, frx, fq); }
;             PG8_LDB(B0, 0, 0); PG8_LDB(B1, 0, 1); PG8_SCHED; PG8_LDA(At, 0, 0); PG8_STAGE(PG8_SA(1, 1), a1 + hstepA, voffA);
;             PG8_WAIT_V(8); PG8_WAIT_L(0); PG8_BAR; PG8_MMA(0, 0, At, B0); PG8_MMA(0, 1, At, B1); PG8_BAR; PG8_SCHED;
;             PG8_LDA(At, 0, 1); PG8_STAGE(PG8_SB(0, 0), b2, voffB); PG8_STAGE(PG8_SB(0, 1), b2 + hstepB, voffB); PG8_STAGE(PG8_SA(0, 0), a2, voffA);
;             PG8_WAIT_V(8); PG8_WAIT_L(0); PG8_BAR; PG8_MMA(1, 0, At, B0); PG8_MMA(1, 1, At, B1); PG8_BAR; PG8_SCHED;
.Lpeel_501:
.Lpeel_500:
	v_add_u32_e32 v80, s91, v173
	s_add_i32 s20, 0, 0x14000
	ds_read_b128 v[132:135], v80
	ds_read_b128 v[136:139], v80 offset:1024
	ds_read_b128 v[142:145], v80 offset:2048
	ds_read_b128 v[158:161], v80 offset:3072
	v_add_u32_e32 v80, s20, v173
	ds_read_b128 v[176:179], v80
	ds_read_b128 v[180:183], v80 offset:1024
	ds_read_b128 v[184:187], v80 offset:2048
	ds_read_b128 v[188:191], v80 offset:3072
	ds_read_b128 v[192:195], v174
	ds_read_b128 v[196:199], v174 offset:1024
	ds_read_b128 v[200:203], v174 offset:2048
	ds_read_b128 v[204:207], v174 offset:3072
	ds_read_b128 v[208:211], v174 offset:4096
	ds_read_b128 v[212:215], v174 offset:5120
	ds_read_b128 v[216:219], v174 offset:6144
	ds_read_b128 v[220:223], v174 offset:7168
	s_add_i32 m0, s79, 0xc000
	s_add_i32 s12, s38, 1
	s_lshr_b32 s18, s12, s76
	s_mul_i32 s19, s53, s18
	s_mul_hi_u32 s21, s52, s18
	s_add_i32 s21, s21, s19
	s_mul_i32 s18, s52, s18
	s_add_u32 s18, s42, s18
	s_addc_u32 s19, s43, s21
	s_and_b32 s12, s12, s83
	s_lshl_b32 s12, s12, 7
	s_add_u32 s12, s18, s12
	s_addc_u32 s19, s19, 0
	s_add_u32 s18, s12, s7
	s_addc_u32 s19, s19, 0
	global_load_lds_dwordx4 v150, s[18:19]
	s_add_i32 m0, s79, 0xe000
	s_nop 0
	global_load_lds_dwordx4 v154, s[18:19]
	s_waitcnt vmcnt(8)
	s_waitcnt lgkmcnt(0)
	s_barrier
	s_setprio 1
	s_waitcnt lgkmcnt(0)
	v_mfma_f32_16x16x32_bf16 v[128:131], v[132:135], v[192:195], 0
	s_add_i32 s0, s38, 2
	v_mfma_f32_16x16x32_bf16 v[124:127], v[142:145], v[192:195], 0
	s_lshr_b32 s1, s0, s76
	v_mfma_f32_16x16x32_bf16 v[112:115], v[132:135], v[200:203], 0
	s_mul_i32 s12, s53, s1
	v_mfma_f32_16x16x32_bf16 v[108:111], v[142:145], v[200:203], 0
	s_mul_hi_u32 s18, s52, s1
	v_mfma_f32_16x16x32_bf16 v[96:99], v[132:135], v[208:211], 0
	s_add_i32 s18, s18, s12
	v_mfma_f32_16x16x32_bf16 v[92:95], v[142:145], v[208:211], 0
	s_mul_i32 s12, s52, s1
	v_mfma_f32_16x16x32_bf16 v[76:79], v[132:135], v[216:219], 0
	s_and_b32 s0, s0, s83
	v_mfma_f32_16x16x32_bf16 v[72:75], v[142:145], v[216:219], 0
	s_lshl_b32 s0, s0, 7
	v_mfma_f32_16x16x32_bf16 v[128:131], v[136:139], v[196:199], v[128:131]
	s_mul_i32 s19, s49, s1
	v_mfma_f32_16x16x32_bf16 v[124:127], v[158:161], v[196:199], v[124:127]
	s_mul_hi_u32 s21, s48, s1
	v_mfma_f32_16x16x32_bf16 v[112:115], v[136:139], v[204:207], v[112:115]
	s_add_i32 s21, s21, s19
	v_mfma_f32_16x16x32_bf16 v[108:111], v[158:161], v[204:207], v[108:111]
	s_mul_i32 s19, s48, s1
	v_mfma_f32_16x16x32_bf16 v[96:99], v[136:139], v[212:215], v[96:99]
	s_add_u32 s12, s42, s12
	v_mfma_f32_16x16x32_bf16 v[92:95], v[158:161], v[212:215], v[92:95]
	s_addc_u32 s18, s43, s18
	v_mfma_f32_16x16x32_bf16 v[76:79], v[136:139], v[220:223], v[76:79]
	s_add_u32 s12, s12, s0
	v_mfma_f32_16x16x32_bf16 v[72:75], v[158:161], v[220:223], v[72:75]
	s_addc_u32 s18, s18, 0
	v_mfma_f32_16x16x32_bf16 v[120:123], v[176:179], v[192:195], 0
	s_add_u32 s19, s40, s19
	v_mfma_f32_16x16x32_bf16 v[116:119], v[184:187], v[192:195], 0
	s_addc_u32 s21, s41, s21
	v_mfma_f32_16x16x32_bf16 v[104:107], v[176:179], v[200:203], 0
	s_add_u32 s19, s19, s0
	v_mfma_f32_16x16x32_bf16 v[100:103], v[184:187], v[200:203], 0
	s_addc_u32 s21, s21, 0
	v_mfma_f32_16x16x32_bf16 v[88:91], v[176:179], v[208:211], 0
	s_cmp_eq_u32 s96, s38
	v_mfma_f32_16x16x32_bf16 v[82:85], v[184:187], v[208:211], 0
	s_cselect_b32 s0, s60, s12
	v_mfma_f32_16x16x32_bf16 v[68:71], v[176:179], v[216:219], 0
	s_cselect_b32 s1, s61, s18
	v_mfma_f32_16x16x32_bf16 v[64:67], v[184:187], v[216:219], 0
	s_cselect_b32 s64, s62, s19
	v_mfma_f32_16x16x32_bf16 v[120:123], v[180:183], v[196:199], v[120:123]
	s_cselect_b32 s65, s63, s21
	v_mfma_f32_16x16x32_bf16 v[116:119], v[188:191], v[196:199], v[116:119]
	v_mfma_f32_16x16x32_bf16 v[104:107], v[180:183], v[204:207], v[104:107]
	v_mfma_f32_16x16x32_bf16 v[100:103], v[188:191], v[204:207], v[100:103]
	v_mfma_f32_16x16x32_bf16 v[88:91], v[180:183], v[212:215], v[88:91]
	v_mfma_f32_16x16x32_bf16 v[82:85], v[188:191], v[212:215], v[82:85]
	v_mfma_f32_16x16x32_bf16 v[68:71], v[180:183], v[220:223], v[68:71]
	v_mfma_f32_16x16x32_bf16 v[64:67], v[188:191], v[220:223], v[64:67]
	s_setprio 0
	s_barrier
	s_add_i32 s12, s91, s78
	s_mov_b32 m0, s12
	ds_read_b128 v[192:195], v174 offset:16384
	ds_read_b128 v[196:199], v174 offset:17408
	ds_read_b128 v[200:203], v174 offset:18432
	ds_read_b128 v[204:207], v174 offset:19456
	ds_read_b128 v[208:211], v174 offset:20480
	ds_read_b128 v[212:215], v174 offset:21504
	ds_read_b128 v[216:219], v174 offset:22528
	ds_read_b128 v[220:223], v174 offset:23552
	global_load_lds_dwordx4 v152, s[64:65]
	s_add_i32 m0, s12, 0x2000
	s_add_u32 s18, s64, s77
	s_addc_u32 s19, s65, 0
	s_add_i32 s12, s20, s78
	global_load_lds_dwordx4 v156, s[64:65]
	s_mov_b32 m0, s12
	s_nop 0
	global_load_lds_dwordx4 v152, s[18:19]
	s_add_i32 m0, s12, 0x2000
	s_nop 0
	global_load_lds_dwordx4 v156, s[18:19]
	s_mov_b32 m0, s79
	s_nop 0
	global_load_lds_dwordx4 v150, s[0:1]
	s_mov_b32 m0, s80
	s_nop 0
	global_load_lds_dwordx4 v154, s[0:1]
	s_waitcnt vmcnt(8)
	s_waitcnt lgkmcnt(0)
	s_barrier
; #define PG8_STAGE(bufoff, gbase, voff) do { _Pragma("unroll") for (int _i = 0; _i < 2; ++_i) \
;         __builtin_amdgcn_global_load_lds((const unsigned*)((const char*)(gbase) + (voff)[_i]), (LAS unsigned*)(lds + (bufoff) + ldsw + _i * 8192), 16, 0, 0); } while (0)
; #define PG8_LDA(dst, b, h) do { _Pragma("unroll") for (int m = 0; m < 4; ++m) _Pragma("unroll") for (int k = 0; k < 2; ++k) dst[m][k] = *(const LAS bf16x8*)(lds + PG8_SA(b, h) + aoff + m * 2048 + k * 1024); } while (0)
; #define PG8_LDB(dst, b, h) do { _Pragma("unroll") for (int n = 0; n < 2; ++n) _Pragma("unroll") for (int k = 0; k < 2; ++k) dst[n][k] = *(const LAS bf16x8*)(lds + PG8_SB(b, h) + boff + n * 2048 + k * 1024); } while (0)
; #define PG8_MMA(ai, bj, At, Bt) do { __builtin_amdgcn_s_setprio(1); _Pragma("unroll") for (int m = 0; m < 4; ++m) _Pragma("unroll") for (int n = 0; n < 2; ++n) _Pragma("unroll") for (int k = 0; k < 2; ++k) \
;         acc[ai][bj][m][n] = __builtin_amdgcn_mfma_f32_16x16x32_bf16(Bt[n][k], At[m][k], acc[ai][bj][m][n], 0, 0, 0); __builtin_amdgcn_s_setprio(0); } while (0)
; #define PG8_WAIT_V(n) asm volatile("s_waitcnt vmcnt(" #n ")" ::: "memory")
; #define PG8_WAIT_L(n) asm volatile("s_waitcnt lgkmcnt(" #n ")" ::: "memory")
; #define PG8_BAR __builtin_amdgcn_s_barrier()
; #define PG8_SCHED __builtin_amdgcn_sched_barrier(0)
; DI void gemm_phase(LAS unsigned char* lds, int ph, unsigned char* ws, unsigned char* wg, int l, const float* pscale, int G, int cidx, int nx) {
;     ...
;             PG8_WAIT_V(8); PG8_WAIT_L(0); PG8_BAR; PG8_MMA(1, 0, At, B0); PG8_MMA(1, 1, At, B1); PG8_BAR; PG8_SCHED;
;             PG8_LDB(B0, 1, 0); PG8_LDB(B1, 1, 1); PG8_SCHED; PG8_LDA(At, 1, 0); PG8_STAGE(PG8_SA(0, 1), a2 + hstepA, voffA);
;             PG8_WAIT_V(8); PG8_WAIT_L(0); PG8_BAR; PG8_MMA(0, 0, At, B0); PG8_MMA(0, 1, At, B1); PG8_BAR; PG8_SCHED;
;             PG8_LDA(At, 1, 1); PG8_STAGE(PG8_SB(1, 0), b3, voffB); PG8_STAGE(PG8_SB(1, 1), b3 + hstepB, voffB); PG8_STAGE(PG8_SA(1, 0), a3, voffA);
	s_setprio 1
	s_waitcnt lgkmcnt(0)
	v_mfma_f32_16x16x32_bf16 v[60:63], v[132:135], v[192:195], 0
	v_mfma_f32_16x16x32_bf16 v[56:59], v[142:145], v[192:195], 0
	v_mfma_f32_16x16x32_bf16 v[44:47], v[132:135], v[200:203], 0
	v_mfma_f32_16x16x32_bf16 v[40:43], v[142:145], v[200:203], 0
	v_mfma_f32_16x16x32_bf16 v[28:31], v[132:135], v[208:211], 0
	v_mfma_f32_16x16x32_bf16 v[24:27], v[142:145], v[208:211], 0
	v_mfma_f32_16x16x32_bf16 v[12:15], v[132:135], v[216:219], 0
	v_mfma_f32_16x16x32_bf16 v[8:11], v[142:145], v[216:219], 0
	v_mfma_f32_16x16x32_bf16 v[60:63], v[136:139], v[196:199], v[60:63]
	v_mfma_f32_16x16x32_bf16 v[56:59], v[158:161], v[196:199], v[56:59]
	v_mfma_f32_16x16x32_bf16 v[44:47], v[136:139], v[204:207], v[44:47]
	v_mfma_f32_16x16x32_bf16 v[40:43], v[158:161], v[204:207], v[40:43]
	v_mfma_f32_16x16x32_bf16 v[28:31], v[136:139], v[212:215], v[28:31]
	v_mfma_f32_16x16x32_bf16 v[24:27], v[158:161], v[212:215], v[24:27]
	v_mfma_f32_16x16x32_bf16 v[12:15], v[136:139], v[220:223], v[12:15]
	v_mfma_f32_16x16x32_bf16 v[8:11], v[158:161], v[220:223], v[8:11]
	v_mfma_f32_16x16x32_bf16 v[52:55], v[176:179], v[192:195], 0
	v_mfma_f32_16x16x32_bf16 v[48:51], v[184:187], v[192:195], 0
	v_mfma_f32_16x16x32_bf16 v[36:39], v[176:179], v[200:203], 0
	v_mfma_f32_16x16x32_bf16 v[32:35], v[184:187], v[200:203], 0
	v_mfma_f32_16x16x32_bf16 v[20:23], v[176:179], v[208:211], 0
	v_mfma_f32_16x16x32_bf16 v[16:19], v[184:187], v[208:211], 0
	v_mfma_f32_16x16x32_bf16 v[4:7], v[176:179], v[216:219], 0
	v_mfma_f32_16x16x32_bf16 v[0:3], v[184:187], v[216:219], 0
	v_mfma_f32_16x16x32_bf16 v[52:55], v[180:183], v[196:199], v[52:55]
	v_mfma_f32_16x16x32_bf16 v[48:51], v[188:191], v[196:199], v[48:51]
	v_mfma_f32_16x16x32_bf16 v[36:39], v[180:183], v[204:207], v[36:39]
	v_mfma_f32_16x16x32_bf16 v[32:35], v[188:191], v[204:207], v[32:35]
	v_mfma_f32_16x16x32_bf16 v[20:23], v[180:183], v[212:215], v[20:23]
	v_mfma_f32_16x16x32_bf16 v[16:19], v[188:191], v[212:215], v[16:19]
	v_mfma_f32_16x16x32_bf16 v[4:7], v[180:183], v[220:223], v[4:7]
	v_mfma_f32_16x16x32_bf16 v[0:3], v[188:191], v[220:223], v[0:3]
	s_setprio 0
	s_barrier
	s_add_i32 s12, 0, 0x18000
	v_add_u32_e32 v80, s12, v173
	s_add_i32 s18, 0, 0x1c000
	ds_read_b128 v[132:135], v80
	ds_read_b128 v[136:139], v80 offset:1024
	ds_read_b128 v[142:145], v80 offset:2048
	ds_read_b128 v[158:161], v80 offset:3072
	v_add_u32_e32 v80, s18, v173
	ds_read_b128 v[176:179], v80
	ds_read_b128 v[180:183], v80 offset:1024
	ds_read_b128 v[184:187], v80 offset:2048
	ds_read_b128 v[188:191], v80 offset:3072
	s_add_u32 s0, s0, s7
	s_addc_u32 s1, s1, 0
	s_mov_b32 m0, s81
	ds_read_b128 v[192:195], v174 offset:32768
	ds_read_b128 v[196:199], v174 offset:33792
	ds_read_b128 v[200:203], v174 offset:34816
	ds_read_b128 v[204:207], v174 offset:35840
	ds_read_b128 v[208:211], v174 offset:36864
	ds_read_b128 v[212:215], v174 offset:37888
	ds_read_b128 v[216:219], v174 offset:38912
	ds_read_b128 v[220:223], v174 offset:39936
	global_load_lds_dwordx4 v150, s[0:1]
	s_mov_b32 m0, s82
	s_nop 0
	global_load_lds_dwordx4 v154, s[0:1]
	s_waitcnt vmcnt(8)
	s_waitcnt lgkmcnt(0)
	s_barrier
	s_setprio 1
	s_waitcnt lgkmcnt(0)
	v_mfma_f32_16x16x32_bf16 v[128:131], v[132:135], v[192:195], v[128:131]
	s_sub_u32 s20, s0, s7
	v_mfma_f32_16x16x32_bf16 v[124:127], v[142:145], v[192:195], v[124:127]
	s_subb_u32 s21, s1, 0
	v_mfma_f32_16x16x32_bf16 v[112:115], v[132:135], v[200:203], v[112:115]
	s_add_u32 s20, s20, s4
	v_mfma_f32_16x16x32_bf16 v[108:111], v[142:145], v[200:203], v[108:111]
	s_addc_u32 s21, s21, s5
	v_mfma_f32_16x16x32_bf16 v[96:99], v[132:135], v[208:211], v[96:99]
	s_add_u32 s0, s64, s4
	v_mfma_f32_16x16x32_bf16 v[92:95], v[142:145], v[208:211], v[92:95]
	s_addc_u32 s1, s65, s5
	v_mfma_f32_16x16x32_bf16 v[76:79], v[132:135], v[216:219], v[76:79]
	v_mfma_f32_16x16x32_bf16 v[72:75], v[142:145], v[216:219], v[72:75]
	v_mfma_f32_16x16x32_bf16 v[128:131], v[136:139], v[196:199], v[128:131]
	v_mfma_f32_16x16x32_bf16 v[124:127], v[158:161], v[196:199], v[124:127]
	v_mfma_f32_16x16x32_bf16 v[112:115], v[136:139], v[204:207], v[112:115]
	v_mfma_f32_16x16x32_bf16 v[108:111], v[158:161], v[204:207], v[108:111]
	v_mfma_f32_16x16x32_bf16 v[96:99], v[136:139], v[212:215], v[96:99]
	v_mfma_f32_16x16x32_bf16 v[92:95], v[158:161], v[212:215], v[92:95]
	v_mfma_f32_16x16x32_bf16 v[76:79], v[136:139], v[220:223], v[76:79]
	v_mfma_f32_16x16x32_bf16 v[72:75], v[158:161], v[220:223], v[72:75]
	v_mfma_f32_16x16x32_bf16 v[120:123], v[176:179], v[192:195], v[120:123]
	v_mfma_f32_16x16x32_bf16 v[116:119], v[184:187], v[192:195], v[116:119]
	v_mfma_f32_16x16x32_bf16 v[104:107], v[176:179], v[200:203], v[104:107]
	v_mfma_f32_16x16x32_bf16 v[100:103], v[184:187], v[200:203], v[100:103]
	v_mfma_f32_16x16x32_bf16 v[86:89], v[176:179], v[208:211], v[88:91]
	v_mfma_f32_16x16x32_bf16 v[82:85], v[184:187], v[208:211], v[82:85]
	v_mfma_f32_16x16x32_bf16 v[68:71], v[176:179], v[216:219], v[68:71]
	v_mfma_f32_16x16x32_bf16 v[64:67], v[184:187], v[216:219], v[64:67]
	v_mfma_f32_16x16x32_bf16 v[120:123], v[180:183], v[196:199], v[120:123]
	v_mfma_f32_16x16x32_bf16 v[116:119], v[188:191], v[196:199], v[116:119]
	v_mfma_f32_16x16x32_bf16 v[104:107], v[180:183], v[204:207], v[104:107]
	v_mfma_f32_16x16x32_bf16 v[100:103], v[188:191], v[204:207], v[100:103]
	v_mfma_f32_16x16x32_bf16 v[88:91], v[180:183], v[212:215], v[86:89]
	v_mfma_f32_16x16x32_bf16 v[84:87], v[188:191], v[212:215], v[82:85]
	v_mfma_f32_16x16x32_bf16 v[68:71], v[180:183], v[220:223], v[68:71]
	v_mfma_f32_16x16x32_bf16 v[64:67], v[188:191], v[220:223], v[64:67]
	s_setprio 0
	s_barrier
; #define PG8_STAGE(bufoff, gbase, voff) do { _Pragma("unroll") for (int _i = 0; _i < 2; ++_i) \
;         __builtin_amdgcn_global_load_lds((const unsigned*)((const char*)(gbase) + (voff)[_i]), (LAS unsigned*)(lds + (bufoff) + ldsw + _i * 8192), 16, 0, 0); } while (0)
; #define PG8_LDA(dst, b, h) do { _Pragma("unroll") for (int m = 0; m < 4; ++m) _Pragma("unroll") for (int k = 0; k < 2; ++k) dst[m][k] = *(const LAS bf16x8*)(lds + PG8_SA(b, h) + aoff + m * 2048 + k * 1024); } while (0)
; #define PG8_LDB(dst, b, h) do { _Pragma("unroll") for (int n = 0; n < 2; ++n) _Pragma("unroll") for (int k = 0; k < 2; ++k) dst[n][k] = *(const LAS bf16x8*)(lds + PG8_SB(b, h) + boff + n * 2048 + k * 1024); } while (0)
; #define PG8_BAR __builtin_amdgcn_s_barrier()
; DI void gemm_phase(LAS unsigned char* lds, int ph, unsigned char* ws, unsigned char* wg, int l, const float* pscale, int G, int cidx, int nx) {
;     ...
;             const char* a1 = PG8_KA(t + 1);
;             const char* a2 = last ? nA : PG8_KA(t + 2); const char* b2 = last ? nB : PG8_KB(t + 2);
;             const char* a3 = a2 + kstep; const char* b3 = b2 + kstep;
;             if (zAb != 0 && t != 0 && (t & ntzm) == 0) { unsigned char* wsx = ws; asm volatile("" : "+s"(wsx)); int frx = fr; asm volatile("" : "+v"(frx)); merge_carry(acc, wsx, cur, (t >> lz) - 1, wr, wc, frx, fq); }
;             PG8_LDB(B0, 0, 0); PG8_LDB(B1, 0, 1); PG8_SCHED; PG8_LDA(At, 0, 0); PG8_STAGE(PG8_SA(1, 1), a1 + hstepA, voffA);
;             PG8_WAIT_V(8); PG8_WAIT_L(0); PG8_BAR; PG8_MMA(0, 0, At, B0); PG8_MMA(0, 1, At, B1); PG8_BAR; PG8_SCHED;
;             PG8_LDA(At, 0, 1); PG8_STAGE(PG8_SB(0, 0), b2, voffB); PG8_STAGE(PG8_SB(0, 1), b2 + hstepB, voffB); PG8_STAGE(PG8_SA(0, 0), a2, voffA);
;             PG8_WAIT_V(8); PG8_WAIT_L(0); PG8_BAR; PG8_MMA(1, 0, At, B0); PG8_MMA(1, 1, At, B1); PG8_BAR; PG8_SCHED;
;             PG8_LDB(B0, 1, 0); PG8_LDB(B1, 1, 1); PG8_SCHED; PG8_LDA(At, 1, 0); PG8_STAGE(PG8_SA(0, 1), a2 + hstepA, voffA);
;             PG8_WAIT_V(8); PG8_WAIT_L(0); PG8_BAR; PG8_MMA(0, 0, At, B0); PG8_MMA(0, 1, At, B1); PG8_BAR; PG8_SCHED;
;             PG8_LDA(At, 1, 1); PG8_STAGE(PG8_SB(1, 0), b3, voffB); PG8_STAGE(PG8_SB(1, 1), b3 + hstepB, voffB); PG8_STAGE(PG8_SA(1, 0), a3, voffA);
;             PG8_WAIT_V(8); PG8_WAIT_L(0); PG8_BAR; PG8_MMA(1, 0, At, B0); PG8_MMA(1, 1, At, B1); PG8_BAR; PG8_SCHED;
;         }
	s_add_i32 s19, s12, s78
	s_mov_b32 m0, s19
	ds_read_b128 v[192:195], v174 offset:49152
	ds_read_b128 v[196:199], v174 offset:50176
	ds_read_b128 v[200:203], v174 offset:51200
	ds_read_b128 v[204:207], v174 offset:52224
	ds_read_b128 v[208:211], v174 offset:53248
	ds_read_b128 v[212:215], v174 offset:54272
	ds_read_b128 v[216:219], v174 offset:55296
	ds_read_b128 v[220:223], v174 offset:56320
	global_load_lds_dwordx4 v152, s[0:1]
	s_add_i32 m0, s19, 0x2000
	s_add_i32 s19, s18, s78
	global_load_lds_dwordx4 v156, s[0:1]
	s_add_u32 s0, s0, s77
	s_addc_u32 s1, s1, 0
	s_mov_b32 m0, s19
	s_nop 0
	global_load_lds_dwordx4 v152, s[0:1]
	s_add_i32 m0, s19, 0x2000
	s_nop 0
	global_load_lds_dwordx4 v156, s[0:1]
	s_mov_b32 m0, s93
	s_nop 0
	global_load_lds_dwordx4 v150, s[20:21]
	s_mov_b32 m0, s94
	s_nop 0
	global_load_lds_dwordx4 v154, s[20:21]
	s_waitcnt vmcnt(8)
	s_waitcnt lgkmcnt(0)
	s_barrier
	s_setprio 1
	s_waitcnt lgkmcnt(0)
	v_mfma_f32_16x16x32_bf16 v[60:63], v[132:135], v[192:195], v[60:63]
	v_mfma_f32_16x16x32_bf16 v[56:59], v[142:145], v[192:195], v[56:59]
	v_mfma_f32_16x16x32_bf16 v[44:47], v[132:135], v[200:203], v[44:47]
	v_mfma_f32_16x16x32_bf16 v[40:43], v[142:145], v[200:203], v[40:43]
	v_mfma_f32_16x16x32_bf16 v[28:31], v[132:135], v[208:211], v[28:31]
	v_mfma_f32_16x16x32_bf16 v[24:27], v[142:145], v[208:211], v[24:27]
	v_mfma_f32_16x16x32_bf16 v[12:15], v[132:135], v[216:219], v[12:15]
	v_mfma_f32_16x16x32_bf16 v[8:11], v[142:145], v[216:219], v[8:11]
	v_mfma_f32_16x16x32_bf16 v[60:63], v[136:139], v[196:199], v[60:63]
	v_mfma_f32_16x16x32_bf16 v[56:59], v[158:161], v[196:199], v[56:59]
	v_mfma_f32_16x16x32_bf16 v[44:47], v[136:139], v[204:207], v[44:47]
	v_mfma_f32_16x16x32_bf16 v[40:43], v[158:161], v[204:207], v[40:43]
	v_mfma_f32_16x16x32_bf16 v[28:31], v[136:139], v[212:215], v[28:31]
	v_mfma_f32_16x16x32_bf16 v[24:27], v[158:161], v[212:215], v[24:27]
	v_mfma_f32_16x16x32_bf16 v[12:15], v[136:139], v[220:223], v[12:15]
	v_mfma_f32_16x16x32_bf16 v[8:11], v[158:161], v[220:223], v[8:11]
	v_mfma_f32_16x16x32_bf16 v[52:55], v[176:179], v[192:195], v[52:55]
	v_mfma_f32_16x16x32_bf16 v[48:51], v[184:187], v[192:195], v[48:51]
	v_mfma_f32_16x16x32_bf16 v[36:39], v[176:179], v[200:203], v[36:39]
	v_mfma_f32_16x16x32_bf16 v[32:35], v[184:187], v[200:203], v[32:35]
	v_mfma_f32_16x16x32_bf16 v[20:23], v[176:179], v[208:211], v[20:23]
	v_mfma_f32_16x16x32_bf16 v[16:19], v[184:187], v[208:211], v[16:19]
	v_mfma_f32_16x16x32_bf16 v[4:7], v[176:179], v[216:219], v[4:7]
	v_mfma_f32_16x16x32_bf16 v[0:3], v[184:187], v[216:219], v[0:3]
	v_mfma_f32_16x16x32_bf16 v[52:55], v[180:183], v[196:199], v[52:55]
	v_mfma_f32_16x16x32_bf16 v[48:51], v[188:191], v[196:199], v[48:51]
	v_mfma_f32_16x16x32_bf16 v[36:39], v[180:183], v[204:207], v[36:39]
	v_mfma_f32_16x16x32_bf16 v[32:35], v[188:191], v[204:207], v[32:35]
	v_mfma_f32_16x16x32_bf16 v[20:23], v[180:183], v[212:215], v[20:23]
	v_mfma_f32_16x16x32_bf16 v[16:19], v[188:191], v[212:215], v[16:19]
	v_mfma_f32_16x16x32_bf16 v[4:7], v[180:183], v[220:223], v[4:7]
	v_mfma_f32_16x16x32_bf16 v[0:3], v[188:191], v[220:223], v[0:3]
	s_setprio 0
	s_barrier
	s_add_i32 s38, s38, 2
	s_cmp_ge_u32 s38, s75
	s_cbranch_scc1 .LBB0_507
	s_branch .LBB0_501
.LBB0_500:
	v_add_u32_e32 v80, s91, v173
	s_add_i32 s20, 0, 0x14000
	ds_read_b128 v[132:135], v80
	ds_read_b128 v[136:139], v80 offset:1024
	ds_read_b128 v[142:145], v80 offset:2048
	ds_read_b128 v[158:161], v80 offset:3072
	v_add_u32_e32 v80, s20, v173
	ds_read_b128 v[176:179], v80
	ds_read_b128 v[180:183], v80 offset:1024
	ds_read_b128 v[184:187], v80 offset:2048
	ds_read_b128 v[188:191], v80 offset:3072
	ds_read_b128 v[192:195], v174
	ds_read_b128 v[196:199], v174 offset:1024
	ds_read_b128 v[200:203], v174 offset:2048
	ds_read_b128 v[204:207], v174 offset:3072
	ds_read_b128 v[208:211], v174 offset:4096
	ds_read_b128 v[212:215], v174 offset:5120
	ds_read_b128 v[216:219], v174 offset:6144
	ds_read_b128 v[220:223], v174 offset:7168
	s_add_i32 m0, s79, 0xc000
	s_add_i32 s12, s38, 1
	s_lshr_b32 s18, s12, s76
	s_mul_i32 s19, s53, s18
	s_mul_hi_u32 s21, s52, s18
	s_add_i32 s21, s21, s19
	s_mul_i32 s18, s52, s18
	s_add_u32 s18, s42, s18
	s_addc_u32 s19, s43, s21
	s_and_b32 s12, s12, s83
	s_lshl_b32 s12, s12, 7
	s_add_u32 s12, s18, s12
	s_addc_u32 s19, s19, 0
	s_add_u32 s18, s12, s7
	s_addc_u32 s19, s19, 0
	global_load_lds_dwordx4 v150, s[18:19]
	s_add_i32 m0, s79, 0xe000
	s_nop 0
	global_load_lds_dwordx4 v154, s[18:19]
	s_waitcnt vmcnt(8)
	s_waitcnt lgkmcnt(0)
	s_barrier
; #define PG8_STAGE(bufoff, gbase, voff) do { _Pragma("unroll") for (int _i = 0; _i < 2; ++_i) \
;         __builtin_amdgcn_global_load_lds((const unsigned*)((const char*)(gbase) + (voff)[_i]), (LAS unsigned*)(lds + (bufoff) + ldsw + _i * 8192), 16, 0, 0); } while (0)
; #define PG8_LDA(dst, b, h) do { _Pragma("unroll") for (int m = 0; m < 4; ++m) _Pragma("unroll") for (int k = 0; k < 2; ++k) dst[m][k] = *(const LAS bf16x8*)(lds + PG8_SA(b, h) + aoff + m * 2048 + k * 1024); } while (0)
; #define PG8_LDB(dst, b, h) do { _Pragma("unroll") for (int n = 0; n < 2; ++n) _Pragma("unroll") for (int k = 0; k < 2; ++k) dst[n][k] = *(const LAS bf16x8*)(lds + PG8_SB(b, h) + boff + n * 2048 + k * 1024); } while (0)
; #define PG8_MMA(ai, bj, At, Bt) do { __builtin_amdgcn_s_setprio(1); _Pragma("unroll") for (int m = 0; m < 4; ++m) _Pragma("unroll") for (int n = 0; n < 2; ++n) _Pragma("unroll") for (int k = 0; k < 2; ++k) \
;         acc[ai][bj][m][n] = __builtin_amdgcn_mfma_f32_16x16x32_bf16(Bt[n][k], At[m][k], acc[ai][bj][m][n], 0, 0, 0); __builtin_amdgcn_s_setprio(0); } while (0)
; DI void gemm_phase(LAS unsigned char* lds, int ph, unsigned char* ws, unsigned char* wg, int l, const float* pscale, int G, int cidx, int nx) {
;     ...
;             const char* a2 = last ? nA : PG8_KA(t + 2); const char* b2 = last ? nB : PG8_KB(t + 2);
;             const char* a3 = a2 + kstep; const char* b3 = b2 + kstep;
;             if (zAb != 0 && t != 0 && (t & ntzm) == 0) { unsigned char* wsx = ws; asm volatile("" : "+s"(wsx)); int frx = fr; asm volatile("" : "+v"(frx)); merge_carry(acc, wsx, cur, (t >> lz) - 1, wr, wc, frx, fq); }
;             PG8_LDB(B0, 0, 0); PG8_LDB(B1, 0, 1); PG8_SCHED; PG8_LDA(At, 0, 0); PG8_STAGE(PG8_SA(1, 1), a1 + hstepA, voffA);
;             PG8_WAIT_V(8); PG8_WAIT_L(0); PG8_BAR; PG8_MMA(0, 0, At, B0); PG8_MMA(0, 1, At, B1); PG8_BAR; PG8_SCHED;
;             PG8_LDA(At, 0, 1); PG8_STAGE(PG8_SB(0, 0), b2, voffB); PG8_STAGE(PG8_SB(0, 1), b2 + hstepB, voffB); PG8_STAGE(PG8_SA(0, 0), a2, voffA);
;             PG8_WAIT_V(8); PG8_WAIT_L(0); PG8_BAR; PG8_MMA(1, 0, At, B0); PG8_MMA(1, 1, At, B1); PG8_BAR; PG8_SCHED;
;             PG8_LDB(B0, 1, 0); PG8_LDB(B1, 1, 1); PG8_SCHED; PG8_LDA(At, 1, 0); PG8_STAGE(PG8_SA(0, 1), a2 + hstepA, voffA);
;             PG8_WAIT_V(8); PG8_WAIT_L(0); PG8_BAR; PG8_MMA(0, 0, At, B0); PG8_MMA(0, 1, At, B1); PG8_BAR; PG8_SCHED;
	s_setprio 1
	s_waitcnt lgkmcnt(0)
	v_mfma_f32_16x16x32_bf16 v[128:131], v[132:135], v[192:195], v[128:131]
	s_add_i32 s0, s38, 2
	v_mfma_f32_16x16x32_bf16 v[124:127], v[142:145], v[192:195], v[124:127]
	s_lshr_b32 s1, s0, s76
	v_mfma_f32_16x16x32_bf16 v[112:115], v[132:135], v[200:203], v[112:115]
	s_mul_i32 s12, s53, s1
	v_mfma_f32_16x16x32_bf16 v[108:111], v[142:145], v[200:203], v[108:111]
	s_mul_hi_u32 s18, s52, s1
	v_mfma_f32_16x16x32_bf16 v[96:99], v[132:135], v[208:211], v[96:99]
	s_add_i32 s18, s18, s12
	v_mfma_f32_16x16x32_bf16 v[92:95], v[142:145], v[208:211], v[92:95]
	s_mul_i32 s12, s52, s1
	v_mfma_f32_16x16x32_bf16 v[76:79], v[132:135], v[216:219], v[76:79]
	s_and_b32 s0, s0, s83
	v_mfma_f32_16x16x32_bf16 v[72:75], v[142:145], v[216:219], v[72:75]
	s_lshl_b32 s0, s0, 7
	v_mfma_f32_16x16x32_bf16 v[128:131], v[136:139], v[196:199], v[128:131]
	s_mul_i32 s19, s49, s1
	v_mfma_f32_16x16x32_bf16 v[124:127], v[158:161], v[196:199], v[124:127]
	s_mul_hi_u32 s21, s48, s1
	v_mfma_f32_16x16x32_bf16 v[112:115], v[136:139], v[204:207], v[112:115]
	s_add_i32 s21, s21, s19
	v_mfma_f32_16x16x32_bf16 v[108:111], v[158:161], v[204:207], v[108:111]
	s_mul_i32 s19, s48, s1
	v_mfma_f32_16x16x32_bf16 v[96:99], v[136:139], v[212:215], v[96:99]
	s_add_u32 s12, s42, s12
	v_mfma_f32_16x16x32_bf16 v[92:95], v[158:161], v[212:215], v[92:95]
	s_addc_u32 s18, s43, s18
	v_mfma_f32_16x16x32_bf16 v[76:79], v[136:139], v[220:223], v[76:79]
	s_add_u32 s12, s12, s0
	v_mfma_f32_16x16x32_bf16 v[72:75], v[158:161], v[220:223], v[72:75]
	s_addc_u32 s18, s18, 0
	v_mfma_f32_16x16x32_bf16 v[120:123], v[176:179], v[192:195], v[120:123]
	s_add_u32 s19, s40, s19
	v_mfma_f32_16x16x32_bf16 v[116:119], v[184:187], v[192:195], v[116:119]
	s_addc_u32 s21, s41, s21
	v_mfma_f32_16x16x32_bf16 v[104:107], v[176:179], v[200:203], v[104:107]
	s_add_u32 s19, s19, s0
	v_mfma_f32_16x16x32_bf16 v[100:103], v[184:187], v[200:203], v[100:103]
	s_addc_u32 s21, s21, 0
	v_mfma_f32_16x16x32_bf16 v[88:91], v[176:179], v[208:211], v[88:91]
	s_cmp_eq_u32 s96, s38
	v_mfma_f32_16x16x32_bf16 v[82:85], v[184:187], v[208:211], v[84:87]
	s_cselect_b32 s0, s60, s12
	v_mfma_f32_16x16x32_bf16 v[68:71], v[176:179], v[216:219], v[68:71]
	s_cselect_b32 s1, s61, s18
	v_mfma_f32_16x16x32_bf16 v[64:67], v[184:187], v[216:219], v[64:67]
	s_cselect_b32 s64, s62, s19
	v_mfma_f32_16x16x32_bf16 v[120:123], v[180:183], v[196:199], v[120:123]
	s_cselect_b32 s65, s63, s21
	v_mfma_f32_16x16x32_bf16 v[116:119], v[188:191], v[196:199], v[116:119]
	v_mfma_f32_16x16x32_bf16 v[104:107], v[180:183], v[204:207], v[104:107]
	v_mfma_f32_16x16x32_bf16 v[100:103], v[188:191], v[204:207], v[100:103]
	v_mfma_f32_16x16x32_bf16 v[88:91], v[180:183], v[212:215], v[88:91]
	v_mfma_f32_16x16x32_bf16 v[82:85], v[188:191], v[212:215], v[82:85]
	v_mfma_f32_16x16x32_bf16 v[68:71], v[180:183], v[220:223], v[68:71]
	v_mfma_f32_16x16x32_bf16 v[64:67], v[188:191], v[220:223], v[64:67]
	s_setprio 0
	s_barrier
	s_add_i32 s12, s91, s78
	s_mov_b32 m0, s12
	ds_read_b128 v[192:195], v174 offset:16384
	ds_read_b128 v[196:199], v174 offset:17408
	ds_read_b128 v[200:203], v174 offset:18432
	ds_read_b128 v[204:207], v174 offset:19456
	ds_read_b128 v[208:211], v174 offset:20480
	ds_read_b128 v[212:215], v174 offset:21504
	ds_read_b128 v[216:219], v174 offset:22528
	ds_read_b128 v[220:223], v174 offset:23552
	global_load_lds_dwordx4 v152, s[64:65]
	s_add_i32 m0, s12, 0x2000
	s_add_u32 s18, s64, s77
	s_addc_u32 s19, s65, 0
	s_add_i32 s12, s20, s78
	global_load_lds_dwordx4 v156, s[64:65]
	s_mov_b32 m0, s12
	s_nop 0
	global_load_lds_dwordx4 v152, s[18:19]
	s_add_i32 m0, s12, 0x2000
	s_nop 0
	global_load_lds_dwordx4 v156, s[18:19]
	s_mov_b32 m0, s79
	s_nop 0
	global_load_lds_dwordx4 v150, s[0:1]
	s_mov_b32 m0, s80
	s_nop 0
	global_load_lds_dwordx4 v154, s[0:1]
	s_waitcnt vmcnt(8)
	s_waitcnt lgkmcnt(0)
	s_barrier
	s_setprio 1
	s_waitcnt lgkmcnt(0)
	v_mfma_f32_16x16x32_bf16 v[60:63], v[132:135], v[192:195], v[60:63]
	v_mfma_f32_16x16x32_bf16 v[56:59], v[142:145], v[192:195], v[56:59]
	v_mfma_f32_16x16x32_bf16 v[44:47], v[132:135], v[200:203], v[44:47]
	v_mfma_f32_16x16x32_bf16 v[40:43], v[142:145], v[200:203], v[40:43]
	v_mfma_f32_16x16x32_bf16 v[28:31], v[132:135], v[208:211], v[28:31]
	v_mfma_f32_16x16x32_bf16 v[24:27], v[142:145], v[208:211], v[24:27]
	v_mfma_f32_16x16x32_bf16 v[12:15], v[132:135], v[216:219], v[12:15]
	v_mfma_f32_16x16x32_bf16 v[8:11], v[142:145], v[216:219], v[8:11]
	v_mfma_f32_16x16x32_bf16 v[60:63], v[136:139], v[196:199], v[60:63]
	v_mfma_f32_16x16x32_bf16 v[56:59], v[158:161], v[196:199], v[56:59]
	v_mfma_f32_16x16x32_bf16 v[44:47], v[136:139], v[204:207], v[44:47]
	v_mfma_f32_16x16x32_bf16 v[40:43], v[158:161], v[204:207], v[40:43]
	v_mfma_f32_16x16x32_bf16 v[28:31], v[136:139], v[212:215], v[28:31]
	v_mfma_f32_16x16x32_bf16 v[24:27], v[158:161], v[212:215], v[24:27]
	v_mfma_f32_16x16x32_bf16 v[12:15], v[136:139], v[220:223], v[12:15]
	v_mfma_f32_16x16x32_bf16 v[8:11], v[158:161], v[220:223], v[8:11]
	v_mfma_f32_16x16x32_bf16 v[52:55], v[176:179], v[192:195], v[52:55]
	v_mfma_f32_16x16x32_bf16 v[48:51], v[184:187], v[192:195], v[48:51]
	v_mfma_f32_16x16x32_bf16 v[36:39], v[176:179], v[200:203], v[36:39]
	v_mfma_f32_16x16x32_bf16 v[32:35], v[184:187], v[200:203], v[32:35]
	v_mfma_f32_16x16x32_bf16 v[20:23], v[176:179], v[208:211], v[20:23]
	v_mfma_f32_16x16x32_bf16 v[16:19], v[184:187], v[208:211], v[16:19]
	v_mfma_f32_16x16x32_bf16 v[4:7], v[176:179], v[216:219], v[4:7]
	v_mfma_f32_16x16x32_bf16 v[0:3], v[184:187], v[216:219], v[0:3]
	v_mfma_f32_16x16x32_bf16 v[52:55], v[180:183], v[196:199], v[52:55]
	v_mfma_f32_16x16x32_bf16 v[48:51], v[188:191], v[196:199], v[48:51]
	v_mfma_f32_16x16x32_bf16 v[36:39], v[180:183], v[204:207], v[36:39]
	v_mfma_f32_16x16x32_bf16 v[32:35], v[188:191], v[204:207], v[32:35]
	v_mfma_f32_16x16x32_bf16 v[20:23], v[180:183], v[212:215], v[20:23]
	v_mfma_f32_16x16x32_bf16 v[16:19], v[188:191], v[212:215], v[16:19]
	v_mfma_f32_16x16x32_bf16 v[4:7], v[180:183], v[220:223], v[4:7]
	v_mfma_f32_16x16x32_bf16 v[0:3], v[188:191], v[220:223], v[0:3]
	s_setprio 0
	s_barrier
; #define PG8_STAGE(bufoff, gbase, voff) do { _Pragma("unroll") for (int _i = 0; _i < 2; ++_i) \
;         __builtin_amdgcn_global_load_lds((const unsigned*)((const char*)(gbase) + (voff)[_i]), (LAS unsigned*)(lds + (bufoff) + ldsw + _i * 8192), 16, 0, 0); } while (0)
; #define PG8_LDA(dst, b, h) do { _Pragma("unroll") for (int m = 0; m < 4; ++m) _Pragma("unroll") for (int k = 0; k < 2; ++k) dst[m][k] = *(const LAS bf16x8*)(lds + PG8_SA(b, h) + aoff + m * 2048 + k * 1024); } while (0)
; #define PG8_LDB(dst, b, h) do { _Pragma("unroll") for (int n = 0; n < 2; ++n) _Pragma("unroll") for (int k = 0; k < 2; ++k) dst[n][k] = *(const LAS bf16x8*)(lds + PG8_SB(b, h) + boff + n * 2048 + k * 1024); } while (0)
; #define PG8_MMA(ai, bj, At, Bt) do { __builtin_amdgcn_s_setprio(1); _Pragma("unroll") for (int m = 0; m < 4; ++m) _Pragma("unroll") for (int n = 0; n < 2; ++n) _Pragma("unroll") for (int k = 0; k < 2; ++k) \
;         acc[ai][bj][m][n] = __builtin_amdgcn_mfma_f32_16x16x32_bf16(Bt[n][k], At[m][k], acc[ai][bj][m][n], 0, 0, 0); __builtin_amdgcn_s_setprio(0); } while (0)
; #define PG8_WAIT_V(n) asm volatile("s_waitcnt vmcnt(" #n ")" ::: "memory")
; #define PG8_WAIT_L(n) asm volatile("s_waitcnt lgkmcnt(" #n ")" ::: "memory")
; #define PG8_BAR __builtin_amdgcn_s_barrier()
; #define PG8_SCHED __builtin_amdgcn_sched_barrier(0)
; DI void gemm_phase(LAS unsigned char* lds, int ph, unsigned char* ws, unsigned char* wg, int l, const float* pscale, int G, int cidx, int nx) {
;     ...
;             PG8_LDB(B0, 1, 0); PG8_LDB(B1, 1, 1); PG8_SCHED; PG8_LDA(At, 1, 0); PG8_STAGE(PG8_SA(0, 1), a2 + hstepA, voffA);
;             PG8_WAIT_V(8); PG8_WAIT_L(0); PG8_BAR; PG8_MMA(0, 0, At, B0); PG8_MMA(0, 1, At, B1); PG8_BAR; PG8_SCHED;
;             PG8_LDA(At, 1, 1); PG8_STAGE(PG8_SB(1, 0), b3, voffB); PG8_STAGE(PG8_SB(1, 1), b3 + hstepB, voffB); PG8_STAGE(PG8_SA(1, 0), a3, voffA);
;             PG8_WAIT_V(8); PG8_WAIT_L(0); PG8_BAR; PG8_MMA(1, 0, At, B0); PG8_MMA(1, 1, At, B1); PG8_BAR; PG8_SCHED;
;         }
	s_add_i32 s12, 0, 0x18000
	v_add_u32_e32 v80, s12, v173
	s_add_i32 s18, 0, 0x1c000
	ds_read_b128 v[132:135], v80
	ds_read_b128 v[136:139], v80 offset:1024
	ds_read_b128 v[142:145], v80 offset:2048
	ds_read_b128 v[158:161], v80 offset:3072
	v_add_u32_e32 v80, s18, v173
	ds_read_b128 v[176:179], v80
	ds_read_b128 v[180:183], v80 offset:1024
	ds_read_b128 v[184:187], v80 offset:2048
	ds_read_b128 v[188:191], v80 offset:3072
	s_add_u32 s0, s0, s7
	s_addc_u32 s1, s1, 0
	s_mov_b32 m0, s81
	ds_read_b128 v[192:195], v174 offset:32768
	ds_read_b128 v[196:199], v174 offset:33792
	ds_read_b128 v[200:203], v174 offset:34816
	ds_read_b128 v[204:207], v174 offset:35840
	ds_read_b128 v[208:211], v174 offset:36864
	ds_read_b128 v[212:215], v174 offset:37888
	ds_read_b128 v[216:219], v174 offset:38912
	ds_read_b128 v[220:223], v174 offset:39936
	global_load_lds_dwordx4 v150, s[0:1]
	s_mov_b32 m0, s82
	s_nop 0
	global_load_lds_dwordx4 v154, s[0:1]
	s_waitcnt vmcnt(8)
	s_waitcnt lgkmcnt(0)
	s_barrier
	s_setprio 1
	s_waitcnt lgkmcnt(0)
	v_mfma_f32_16x16x32_bf16 v[128:131], v[132:135], v[192:195], v[128:131]
	s_sub_u32 s20, s0, s7
	v_mfma_f32_16x16x32_bf16 v[124:127], v[142:145], v[192:195], v[124:127]
	s_subb_u32 s21, s1, 0
	v_mfma_f32_16x16x32_bf16 v[112:115], v[132:135], v[200:203], v[112:115]
	s_add_u32 s20, s20, s4
	v_mfma_f32_16x16x32_bf16 v[108:111], v[142:145], v[200:203], v[108:111]
	s_addc_u32 s21, s21, s5
	v_mfma_f32_16x16x32_bf16 v[96:99], v[132:135], v[208:211], v[96:99]
	s_add_u32 s0, s64, s4
	v_mfma_f32_16x16x32_bf16 v[92:95], v[142:145], v[208:211], v[92:95]
	s_addc_u32 s1, s65, s5
	v_mfma_f32_16x16x32_bf16 v[76:79], v[132:135], v[216:219], v[76:79]
	v_mfma_f32_16x16x32_bf16 v[72:75], v[142:145], v[216:219], v[72:75]
	v_mfma_f32_16x16x32_bf16 v[128:131], v[136:139], v[196:199], v[128:131]
	v_mfma_f32_16x16x32_bf16 v[124:127], v[158:161], v[196:199], v[124:127]
	v_mfma_f32_16x16x32_bf16 v[112:115], v[136:139], v[204:207], v[112:115]
	v_mfma_f32_16x16x32_bf16 v[108:111], v[158:161], v[204:207], v[108:111]
	v_mfma_f32_16x16x32_bf16 v[96:99], v[136:139], v[212:215], v[96:99]
	v_mfma_f32_16x16x32_bf16 v[92:95], v[158:161], v[212:215], v[92:95]
	v_mfma_f32_16x16x32_bf16 v[76:79], v[136:139], v[220:223], v[76:79]
	v_mfma_f32_16x16x32_bf16 v[72:75], v[158:161], v[220:223], v[72:75]
	v_mfma_f32_16x16x32_bf16 v[120:123], v[176:179], v[192:195], v[120:123]
	v_mfma_f32_16x16x32_bf16 v[116:119], v[184:187], v[192:195], v[116:119]
	v_mfma_f32_16x16x32_bf16 v[104:107], v[176:179], v[200:203], v[104:107]
	v_mfma_f32_16x16x32_bf16 v[100:103], v[184:187], v[200:203], v[100:103]
	v_mfma_f32_16x16x32_bf16 v[86:89], v[176:179], v[208:211], v[88:91]
	v_mfma_f32_16x16x32_bf16 v[82:85], v[184:187], v[208:211], v[82:85]
	v_mfma_f32_16x16x32_bf16 v[68:71], v[176:179], v[216:219], v[68:71]
	v_mfma_f32_16x16x32_bf16 v[64:67], v[184:187], v[216:219], v[64:67]
	v_mfma_f32_16x16x32_bf16 v[120:123], v[180:183], v[196:199], v[120:123]
	v_mfma_f32_16x16x32_bf16 v[116:119], v[188:191], v[196:199], v[116:119]
	v_mfma_f32_16x16x32_bf16 v[104:107], v[180:183], v[204:207], v[104:107]
	v_mfma_f32_16x16x32_bf16 v[100:103], v[188:191], v[204:207], v[100:103]
	v_mfma_f32_16x16x32_bf16 v[88:91], v[180:183], v[212:215], v[86:89]
	v_mfma_f32_16x16x32_bf16 v[84:87], v[188:191], v[212:215], v[82:85]
	v_mfma_f32_16x16x32_bf16 v[68:71], v[180:183], v[220:223], v[68:71]
	v_mfma_f32_16x16x32_bf16 v[64:67], v[188:191], v[220:223], v[64:67]
	s_setprio 0
	s_barrier
	s_add_i32 s19, s12, s78
	s_mov_b32 m0, s19
	ds_read_b128 v[192:195], v174 offset:49152
	ds_read_b128 v[196:199], v174 offset:50176
	ds_read_b128 v[200:203], v174 offset:51200
	ds_read_b128 v[204:207], v174 offset:52224
	ds_read_b128 v[208:211], v174 offset:53248
	ds_read_b128 v[212:215], v174 offset:54272
	ds_read_b128 v[216:219], v174 offset:55296
	ds_read_b128 v[220:223], v174 offset:56320
	global_load_lds_dwordx4 v152, s[0:1]
	s_add_i32 m0, s19, 0x2000
	s_add_i32 s19, s18, s78
	global_load_lds_dwordx4 v156, s[0:1]
	s_add_u32 s0, s0, s77
	s_addc_u32 s1, s1, 0
	s_mov_b32 m0, s19
	s_nop 0
	global_load_lds_dwordx4 v152, s[0:1]
	s_add_i32 m0, s19, 0x2000
	s_nop 0
	global_load_lds_dwordx4 v156, s[0:1]
	s_mov_b32 m0, s93
	s_nop 0
	global_load_lds_dwordx4 v150, s[20:21]
	s_mov_b32 m0, s94
	s_nop 0
	global_load_lds_dwordx4 v154, s[20:21]
	s_waitcnt vmcnt(8)
	s_waitcnt lgkmcnt(0)
	s_barrier
	s_setprio 1
	s_waitcnt lgkmcnt(0)
	v_mfma_f32_16x16x32_bf16 v[60:63], v[132:135], v[192:195], v[60:63]
	v_mfma_f32_16x16x32_bf16 v[56:59], v[142:145], v[192:195], v[56:59]
	v_mfma_f32_16x16x32_bf16 v[44:47], v[132:135], v[200:203], v[44:47]
	v_mfma_f32_16x16x32_bf16 v[40:43], v[142:145], v[200:203], v[40:43]
	v_mfma_f32_16x16x32_bf16 v[28:31], v[132:135], v[208:211], v[28:31]
	v_mfma_f32_16x16x32_bf16 v[24:27], v[142:145], v[208:211], v[24:27]
	v_mfma_f32_16x16x32_bf16 v[12:15], v[132:135], v[216:219], v[12:15]
	v_mfma_f32_16x16x32_bf16 v[8:11], v[142:145], v[216:219], v[8:11]
	v_mfma_f32_16x16x32_bf16 v[60:63], v[136:139], v[196:199], v[60:63]
	v_mfma_f32_16x16x32_bf16 v[56:59], v[158:161], v[196:199], v[56:59]
	v_mfma_f32_16x16x32_bf16 v[44:47], v[136:139], v[204:207], v[44:47]
	v_mfma_f32_16x16x32_bf16 v[40:43], v[158:161], v[204:207], v[40:43]
	v_mfma_f32_16x16x32_bf16 v[28:31], v[136:139], v[212:215], v[28:31]
	v_mfma_f32_16x16x32_bf16 v[24:27], v[158:161], v[212:215], v[24:27]
	v_mfma_f32_16x16x32_bf16 v[12:15], v[136:139], v[220:223], v[12:15]
	v_mfma_f32_16x16x32_bf16 v[8:11], v[158:161], v[220:223], v[8:11]
	v_mfma_f32_16x16x32_bf16 v[52:55], v[176:179], v[192:195], v[52:55]
	v_mfma_f32_16x16x32_bf16 v[48:51], v[184:187], v[192:195], v[48:51]
	v_mfma_f32_16x16x32_bf16 v[36:39], v[176:179], v[200:203], v[36:39]
	v_mfma_f32_16x16x32_bf16 v[32:35], v[184:187], v[200:203], v[32:35]
	v_mfma_f32_16x16x32_bf16 v[20:23], v[176:179], v[208:211], v[20:23]
	v_mfma_f32_16x16x32_bf16 v[16:19], v[184:187], v[208:211], v[16:19]
	v_mfma_f32_16x16x32_bf16 v[4:7], v[176:179], v[216:219], v[4:7]
	v_mfma_f32_16x16x32_bf16 v[0:3], v[184:187], v[216:219], v[0:3]
	v_mfma_f32_16x16x32_bf16 v[52:55], v[180:183], v[196:199], v[52:55]
	v_mfma_f32_16x16x32_bf16 v[48:51], v[188:191], v[196:199], v[48:51]
	v_mfma_f32_16x16x32_bf16 v[36:39], v[180:183], v[204:207], v[36:39]
	v_mfma_f32_16x16x32_bf16 v[32:35], v[188:191], v[204:207], v[32:35]
	v_mfma_f32_16x16x32_bf16 v[20:23], v[180:183], v[212:215], v[20:23]
	v_mfma_f32_16x16x32_bf16 v[16:19], v[188:191], v[212:215], v[16:19]
	v_mfma_f32_16x16x32_bf16 v[4:7], v[180:183], v[220:223], v[4:7]
	v_mfma_f32_16x16x32_bf16 v[0:3], v[188:191], v[220:223], v[0:3]
	s_setprio 0
	s_barrier
	s_add_i32 s38, s38, 2
	s_cmp_ge_u32 s38, s75
	s_cbranch_scc1 .LBB0_507
; DI float bflo(unsigned u) { return __uint_as_float(u << 16); }
; DI float bfhi(unsigned u) { return __uint_as_float(u & 0xffff0000u); }
; #define PG8_STAGE(bufoff, gbase, voff) do { _Pragma("unroll") for (int _i = 0; _i < 2; ++_i) \
;         __builtin_amdgcn_global_load_lds((const unsigned*)((const char*)(gbase) + (voff)[_i]), (LAS unsigned*)(lds + (bufoff) + ldsw + _i * 8192), 16, 0, 0); } while (0)
; #define PG8_LDA(dst, b, h) do { _Pragma("unroll") for (int m = 0; m < 4; ++m) _Pragma("unroll") for (int k = 0; k < 2; ++k) dst[m][k] = *(const LAS bf16x8*)(lds + PG8_SA(b, h) + aoff + m * 2048 + k * 1024); } while (0)
; #define PG8_SCHED __builtin_amdgcn_sched_barrier(0)
; DI void merge_carry(f32x4 (&acc)[2][2][4][2], unsigned char* ws, const Unit& u, int z, int wr, int wc, int fr, int fq) {
;     ...
;     const bf16_t* gate = (const bf16_t*)(ws + WS_PROJ) + PC_G + (size_t)z * D;
; #pragma unroll
;     for (int ai = 0; ai < 2; ++ai)
; #pragma unroll
;         for (int m = 0; m < 4; ++m) { const size_t row = (size_t)(row0 + ai * HALF + m * 16);
; #pragma unroll
;             for (int bj = 0; bj < 2; ++bj) { const int col = col0 + bj * 32;
;                 const u32x4 gw = *(const u32x4*)(gate + row * DIN + col), hw = *(const u32x4*)(gate + row * DIN + D + col);
;                 const float ga[8] = {bflo(gw.x), bfhi(gw.x), bflo(gw.y), bfhi(gw.y), bflo(gw.z), bfhi(gw.z), bflo(gw.w), bfhi(gw.w)};
;                 const float gb[8] = {bflo(hw.x), bfhi(hw.x), bflo(hw.y), bfhi(hw.y), bflo(hw.z), bfhi(hw.z), bflo(hw.w), bfhi(hw.w)};
;                 float f[8];
; #pragma unroll
;                 for (int j = 0; j < 8; ++j) f[j] = gb[j] * __builtin_amdgcn_rcpf(ga[j]);
;                 acc[ai][bj][m][0] = acc[ai][bj][m][0] * (f32x4){f[0], f[1], f[2], f[3]}; acc[ai][bj][m][1] = acc[ai][bj][m][1] * (f32x4){f[4], f[5], f[6], f[7]};
;                 asm volatile("" ::: "memory"); } }
; DI void gemm_phase(LAS unsigned char* lds, int ph, unsigned char* ws, unsigned char* wg, int l, const float* pscale, int G, int cidx, int nx) {
;     ...
;             if (zAb != 0 && t != 0 && (t & ntzm) == 0) { unsigned char* wsx = ws; asm volatile("" : "+s"(wsx)); int frx = fr; asm volatile("" : "+v"(frx)); merge_carry(acc, wsx, cur, (t >> lz) - 1, wr, wc, frx, fq); }
;             PG8_LDB(B0, 0, 0); PG8_LDB(B1, 0, 1); PG8_SCHED; PG8_LDA(At, 0, 0); PG8_STAGE(PG8_SA(1, 1), a1 + hstepA, voffA);
.LBB0_501:
	s_and_b64 vcc, exec, s[50:51]
	s_cbranch_vccz .LBB0_500
	s_cmp_lg_u32 s38, 0
	s_cselect_b64 s[18:19], -1, 0
	s_and_b64 s[18:19], s[50:51], s[18:19]
	s_and_b32 s12, s38, s83
	s_cmp_eq_u32 s12, 0
	s_cselect_b64 s[20:21], -1, 0
	s_and_b64 s[18:19], s[18:19], s[20:21]
	s_andn2_b64 vcc, exec, s[18:19]
	s_cbranch_vccnz .LBB0_500
	s_lshr_b32 s20, s38, s76
	s_ashr_i32 s21, s20, 31
	s_mov_b64 s[18:19], s[46:47]
	s_lshl_b64 s[20:21], s[20:21], 11
	s_add_u32 s12, s18, s20
	s_addc_u32 s19, s19, s21
	v_mov_b32_e32 v80, v149
	s_add_u32 s18, s12, 0x10401c00
	s_addc_u32 s19, s19, 0
	v_add_u32_e32 v80, s69, v80
	v_mov_b64_e32 v[82:83], s[18:19]
	s_mov_b64 s[18:19], 0x3c000
	s_mov_b64 s[20:21], 0x12c000
	s_mov_b32 s12, 0xffff0000
	v_mad_i64_i32 v[132:133], vcc, v80, s14, v[82:83]
	v_lshlrev_b64 v[136:137], 1, v[140:141]
	v_lshl_add_u64 v[82:83], v[132:133], 0, v[136:137]
	global_load_dwordx4 v[132:135], v[82:83], off offset:0
	global_load_dwordx4 v[136:139], v[82:83], off offset:2048
	global_load_dwordx4 v[142:145], v[82:83], off offset:64
	global_load_dwordx4 v[158:161], v[82:83], off offset:2112
	v_lshl_add_u64 v[82:83], v[82:83], 0, s[18:19]
	global_load_dwordx4 v[176:179], v[82:83], off offset:0
	global_load_dwordx4 v[180:183], v[82:83], off offset:2048
	global_load_dwordx4 v[184:187], v[82:83], off offset:64
	global_load_dwordx4 v[188:191], v[82:83], off offset:2112
	v_lshl_add_u64 v[82:83], v[82:83], 0, s[18:19]
	global_load_dwordx4 v[192:195], v[82:83], off offset:0
	global_load_dwordx4 v[196:199], v[82:83], off offset:2048
	global_load_dwordx4 v[200:203], v[82:83], off offset:64
	global_load_dwordx4 v[204:207], v[82:83], off offset:2112
	v_lshl_add_u64 v[82:83], v[82:83], 0, s[18:19]
	global_load_dwordx4 v[208:211], v[82:83], off offset:0
	global_load_dwordx4 v[212:215], v[82:83], off offset:2048
	s_waitcnt vmcnt(12)
	v_lshlrev_b32_e32 v216, 16, v132
	v_and_b32_e32 v217, s12, v132
	v_lshlrev_b32_e32 v218, 16, v133
	v_and_b32_e32 v219, s12, v133
	v_lshlrev_b32_e32 v220, 16, v134
	v_and_b32_e32 v221, s12, v134
	v_lshlrev_b32_e32 v222, 16, v135
	v_and_b32_e32 v223, s12, v135
	v_rcp_f32_e32 v216, v216
	v_rcp_f32_e32 v217, v217
	v_rcp_f32_e32 v218, v218
	v_rcp_f32_e32 v219, v219
	v_rcp_f32_e32 v220, v220
	v_rcp_f32_e32 v221, v221
	v_rcp_f32_e32 v222, v222
	v_rcp_f32_e32 v223, v223
	v_lshlrev_b32_e32 v132, 16, v136
	v_and_b32_e32 v133, s12, v136
	v_lshlrev_b32_e32 v134, 16, v137
	v_and_b32_e32 v135, s12, v137
	v_lshlrev_b32_e32 v136, 16, v138
	v_and_b32_e32 v137, s12, v138
	v_lshlrev_b32_e32 v138, 16, v139
	v_and_b32_e32 v139, s12, v139
	v_pk_mul_f32 v[216:217], v[216:217], v[132:133]
	v_pk_mul_f32 v[218:219], v[218:219], v[134:135]
	v_pk_mul_f32 v[220:221], v[220:221], v[136:137]
	v_pk_mul_f32 v[222:223], v[222:223], v[138:139]
	v_pk_mul_f32 v[128:129], v[128:129], v[216:217]
	v_pk_mul_f32 v[130:131], v[130:131], v[218:219]
	v_pk_mul_f32 v[124:125], v[124:125], v[220:221]
	v_pk_mul_f32 v[126:127], v[126:127], v[222:223]
	global_load_dwordx4 v[132:135], v[82:83], off offset:64
	global_load_dwordx4 v[136:139], v[82:83], off offset:2112
	v_lshl_add_u64 v[82:83], v[82:83], 0, s[20:21]
	s_waitcnt vmcnt(12)
	v_lshlrev_b32_e32 v216, 16, v142
	v_and_b32_e32 v217, s12, v142
	v_lshlrev_b32_e32 v218, 16, v143
	v_and_b32_e32 v219, s12, v143
	v_lshlrev_b32_e32 v220, 16, v144
	v_and_b32_e32 v221, s12, v144
	v_lshlrev_b32_e32 v222, 16, v145
	v_and_b32_e32 v223, s12, v145
	v_rcp_f32_e32 v216, v216
	v_rcp_f32_e32 v217, v217
	v_rcp_f32_e32 v218, v218
	v_rcp_f32_e32 v219, v219
	v_rcp_f32_e32 v220, v220
	v_rcp_f32_e32 v221, v221
	v_rcp_f32_e32 v222, v222
	v_rcp_f32_e32 v223, v223
	v_lshlrev_b32_e32 v142, 16, v158
	v_and_b32_e32 v143, s12, v158
	v_lshlrev_b32_e32 v144, 16, v159
	v_and_b32_e32 v145, s12, v159
	v_lshlrev_b32_e32 v158, 16, v160
	v_and_b32_e32 v159, s12, v160
	v_lshlrev_b32_e32 v160, 16, v161
	v_and_b32_e32 v161, s12, v161
	v_pk_mul_f32 v[216:217], v[216:217], v[142:143]
	v_pk_mul_f32 v[218:219], v[218:219], v[144:145]
	v_pk_mul_f32 v[220:221], v[220:221], v[158:159]
	v_pk_mul_f32 v[222:223], v[222:223], v[160:161]
	v_pk_mul_f32 v[120:121], v[120:121], v[216:217]
	v_pk_mul_f32 v[122:123], v[122:123], v[218:219]
	v_pk_mul_f32 v[116:117], v[116:117], v[220:221]
	v_pk_mul_f32 v[118:119], v[118:119], v[222:223]
	global_load_dwordx4 v[142:145], v[82:83], off offset:0
	global_load_dwordx4 v[158:161], v[82:83], off offset:2048
	s_waitcnt vmcnt(12)
	v_lshlrev_b32_e32 v216, 16, v176
	v_and_b32_e32 v217, s12, v176
	v_lshlrev_b32_e32 v218, 16, v177
	v_and_b32_e32 v219, s12, v177
	v_lshlrev_b32_e32 v220, 16, v178
	v_and_b32_e32 v221, s12, v178
	v_lshlrev_b32_e32 v222, 16, v179
	v_and_b32_e32 v223, s12, v179
	v_rcp_f32_e32 v216, v216
	v_rcp_f32_e32 v217, v217
	v_rcp_f32_e32 v218, v218
	v_rcp_f32_e32 v219, v219
	v_rcp_f32_e32 v220, v220
	v_rcp_f32_e32 v221, v221
	v_rcp_f32_e32 v222, v222
	v_rcp_f32_e32 v223, v223
	v_lshlrev_b32_e32 v176, 16, v180
	v_and_b32_e32 v177, s12, v180
	v_lshlrev_b32_e32 v178, 16, v181
	v_and_b32_e32 v179, s12, v181
	v_lshlrev_b32_e32 v180, 16, v182
	v_and_b32_e32 v181, s12, v182
	v_lshlrev_b32_e32 v182, 16, v183
	v_and_b32_e32 v183, s12, v183
	v_pk_mul_f32 v[216:217], v[216:217], v[176:177]
	v_pk_mul_f32 v[218:219], v[218:219], v[178:179]
	v_pk_mul_f32 v[220:221], v[220:221], v[180:181]
	v_pk_mul_f32 v[222:223], v[222:223], v[182:183]
	v_pk_mul_f32 v[112:113], v[112:113], v[216:217]
	v_pk_mul_f32 v[114:115], v[114:115], v[218:219]
	v_pk_mul_f32 v[108:109], v[108:109], v[220:221]
	v_pk_mul_f32 v[110:111], v[110:111], v[222:223]
	global_load_dwordx4 v[176:179], v[82:83], off offset:64
	global_load_dwordx4 v[180:183], v[82:83], off offset:2112
	v_lshl_add_u64 v[82:83], v[82:83], 0, s[18:19]
	s_waitcnt vmcnt(12)
; DI float bflo(unsigned u) { return __uint_as_float(u << 16); }
; DI float bfhi(unsigned u) { return __uint_as_float(u & 0xffff0000u); }
; DI void merge_carry(f32x4 (&acc)[2][2][4][2], unsigned char* ws, const Unit& u, int z, int wr, int wc, int fr, int fq) {
;     ...
;             for (int bj = 0; bj < 2; ++bj) { const int col = col0 + bj * 32;
;                 const u32x4 gw = *(const u32x4*)(gate + row * DIN + col), hw = *(const u32x4*)(gate + row * DIN + D + col);
;                 const float ga[8] = {bflo(gw.x), bfhi(gw.x), bflo(gw.y), bfhi(gw.y), bflo(gw.z), bfhi(gw.z), bflo(gw.w), bfhi(gw.w)};
;                 const float gb[8] = {bflo(hw.x), bfhi(hw.x), bflo(hw.y), bfhi(hw.y), bflo(hw.z), bfhi(hw.z), bflo(hw.w), bfhi(hw.w)};
;                 float f[8];
; #pragma unroll
;                 for (int j = 0; j < 8; ++j) f[j] = gb[j] * __builtin_amdgcn_rcpf(ga[j]);
;                 acc[ai][bj][m][0] = acc[ai][bj][m][0] * (f32x4){f[0], f[1], f[2], f[3]}; acc[ai][bj][m][1] = acc[ai][bj][m][1] * (f32x4){f[4], f[5], f[6], f[7]};
;                 asm volatile("" ::: "memory"); } }
	v_lshlrev_b32_e32 v216, 16, v184
	v_and_b32_e32 v217, s12, v184
	v_lshlrev_b32_e32 v218, 16, v185
	v_and_b32_e32 v219, s12, v185
	v_lshlrev_b32_e32 v220, 16, v186
	v_and_b32_e32 v221, s12, v186
	v_lshlrev_b32_e32 v222, 16, v187
	v_and_b32_e32 v223, s12, v187
	v_rcp_f32_e32 v216, v216
	v_rcp_f32_e32 v217, v217
	v_rcp_f32_e32 v218, v218
	v_rcp_f32_e32 v219, v219
	v_rcp_f32_e32 v220, v220
	v_rcp_f32_e32 v221, v221
	v_rcp_f32_e32 v222, v222
	v_rcp_f32_e32 v223, v223
	v_lshlrev_b32_e32 v184, 16, v188
	v_and_b32_e32 v185, s12, v188
	v_lshlrev_b32_e32 v186, 16, v189
	v_and_b32_e32 v187, s12, v189
	v_lshlrev_b32_e32 v188, 16, v190
	v_and_b32_e32 v189, s12, v190
	v_lshlrev_b32_e32 v190, 16, v191
	v_and_b32_e32 v191, s12, v191
	v_pk_mul_f32 v[216:217], v[216:217], v[184:185]
	v_pk_mul_f32 v[218:219], v[218:219], v[186:187]
	v_pk_mul_f32 v[220:221], v[220:221], v[188:189]
	v_pk_mul_f32 v[222:223], v[222:223], v[190:191]
	v_pk_mul_f32 v[104:105], v[104:105], v[216:217]
	v_pk_mul_f32 v[106:107], v[106:107], v[218:219]
	v_pk_mul_f32 v[100:101], v[100:101], v[220:221]
	v_pk_mul_f32 v[102:103], v[102:103], v[222:223]
	global_load_dwordx4 v[184:187], v[82:83], off offset:0
	global_load_dwordx4 v[188:191], v[82:83], off offset:2048
	s_waitcnt vmcnt(12)
	v_lshlrev_b32_e32 v216, 16, v192
	v_and_b32_e32 v217, s12, v192
	v_lshlrev_b32_e32 v218, 16, v193
	v_and_b32_e32 v219, s12, v193
	v_lshlrev_b32_e32 v220, 16, v194
	v_and_b32_e32 v221, s12, v194
	v_lshlrev_b32_e32 v222, 16, v195
	v_and_b32_e32 v223, s12, v195
	v_rcp_f32_e32 v216, v216
	v_rcp_f32_e32 v217, v217
	v_rcp_f32_e32 v218, v218
	v_rcp_f32_e32 v219, v219
	v_rcp_f32_e32 v220, v220
	v_rcp_f32_e32 v221, v221
	v_rcp_f32_e32 v222, v222
	v_rcp_f32_e32 v223, v223
	v_lshlrev_b32_e32 v192, 16, v196
	v_and_b32_e32 v193, s12, v196
	v_lshlrev_b32_e32 v194, 16, v197
	v_and_b32_e32 v195, s12, v197
	v_lshlrev_b32_e32 v196, 16, v198
	v_and_b32_e32 v197, s12, v198
	v_lshlrev_b32_e32 v198, 16, v199
	v_and_b32_e32 v199, s12, v199
	v_pk_mul_f32 v[216:217], v[216:217], v[192:193]
	v_pk_mul_f32 v[218:219], v[218:219], v[194:195]
	v_pk_mul_f32 v[220:221], v[220:221], v[196:197]
	v_pk_mul_f32 v[222:223], v[222:223], v[198:199]
	v_pk_mul_f32 v[96:97], v[96:97], v[216:217]
	v_pk_mul_f32 v[98:99], v[98:99], v[218:219]
	v_pk_mul_f32 v[92:93], v[92:93], v[220:221]
	v_pk_mul_f32 v[94:95], v[94:95], v[222:223]
	global_load_dwordx4 v[192:195], v[82:83], off offset:64
	global_load_dwordx4 v[196:199], v[82:83], off offset:2112
	v_lshl_add_u64 v[82:83], v[82:83], 0, s[18:19]
	s_waitcnt vmcnt(12)
	v_lshlrev_b32_e32 v216, 16, v200
	v_and_b32_e32 v217, s12, v200
	v_lshlrev_b32_e32 v218, 16, v201
	v_and_b32_e32 v219, s12, v201
	v_lshlrev_b32_e32 v220, 16, v202
	v_and_b32_e32 v221, s12, v202
	v_lshlrev_b32_e32 v222, 16, v203
	v_and_b32_e32 v223, s12, v203
	v_rcp_f32_e32 v216, v216
	v_rcp_f32_e32 v217, v217
	v_rcp_f32_e32 v218, v218
	v_rcp_f32_e32 v219, v219
	v_rcp_f32_e32 v220, v220
	v_rcp_f32_e32 v221, v221
	v_rcp_f32_e32 v222, v222
	v_rcp_f32_e32 v223, v223
	v_lshlrev_b32_e32 v200, 16, v204
	v_and_b32_e32 v201, s12, v204
	v_lshlrev_b32_e32 v202, 16, v205
	v_and_b32_e32 v203, s12, v205
	v_lshlrev_b32_e32 v204, 16, v206
	v_and_b32_e32 v205, s12, v206
	v_lshlrev_b32_e32 v206, 16, v207
	v_and_b32_e32 v207, s12, v207
	v_pk_mul_f32 v[216:217], v[216:217], v[200:201]
	v_pk_mul_f32 v[218:219], v[218:219], v[202:203]
	v_pk_mul_f32 v[220:221], v[220:221], v[204:205]
	v_pk_mul_f32 v[222:223], v[222:223], v[206:207]
	v_pk_mul_f32 v[88:89], v[88:89], v[216:217]
	v_pk_mul_f32 v[90:91], v[90:91], v[218:219]
	v_pk_mul_f32 v[84:85], v[84:85], v[220:221]
	v_pk_mul_f32 v[86:87], v[86:87], v[222:223]
	global_load_dwordx4 v[200:203], v[82:83], off offset:0
	global_load_dwordx4 v[204:207], v[82:83], off offset:2048
	s_waitcnt vmcnt(12)
	v_lshlrev_b32_e32 v216, 16, v208
	v_and_b32_e32 v217, s12, v208
	v_lshlrev_b32_e32 v218, 16, v209
	v_and_b32_e32 v219, s12, v209
	v_lshlrev_b32_e32 v220, 16, v210
	v_and_b32_e32 v221, s12, v210
	v_lshlrev_b32_e32 v222, 16, v211
	v_and_b32_e32 v223, s12, v211
	v_rcp_f32_e32 v216, v216
	v_rcp_f32_e32 v217, v217
	v_rcp_f32_e32 v218, v218
	v_rcp_f32_e32 v219, v219
	v_rcp_f32_e32 v220, v220
	v_rcp_f32_e32 v221, v221
	v_rcp_f32_e32 v222, v222
	v_rcp_f32_e32 v223, v223
	v_lshlrev_b32_e32 v208, 16, v212
	v_and_b32_e32 v209, s12, v212
	v_lshlrev_b32_e32 v210, 16, v213
	v_and_b32_e32 v211, s12, v213
	v_lshlrev_b32_e32 v212, 16, v214
	v_and_b32_e32 v213, s12, v214
	v_lshlrev_b32_e32 v214, 16, v215
	v_and_b32_e32 v215, s12, v215
	v_pk_mul_f32 v[216:217], v[216:217], v[208:209]
	v_pk_mul_f32 v[218:219], v[218:219], v[210:211]
	v_pk_mul_f32 v[220:221], v[220:221], v[212:213]
	v_pk_mul_f32 v[222:223], v[222:223], v[214:215]
	v_pk_mul_f32 v[76:77], v[76:77], v[216:217]
	v_pk_mul_f32 v[78:79], v[78:79], v[218:219]
	v_pk_mul_f32 v[72:73], v[72:73], v[220:221]
	v_pk_mul_f32 v[74:75], v[74:75], v[222:223]
	global_load_dwordx4 v[208:211], v[82:83], off offset:64
	global_load_dwordx4 v[212:215], v[82:83], off offset:2112
	v_lshl_add_u64 v[82:83], v[82:83], 0, s[18:19]
	s_waitcnt vmcnt(12)
; DI float bflo(unsigned u) { return __uint_as_float(u << 16); }
; DI float bfhi(unsigned u) { return __uint_as_float(u & 0xffff0000u); }
; DI void merge_carry(f32x4 (&acc)[2][2][4][2], unsigned char* ws, const Unit& u, int z, int wr, int wc, int fr, int fq) {
;     ...
;             for (int bj = 0; bj < 2; ++bj) { const int col = col0 + bj * 32;
;                 const u32x4 gw = *(const u32x4*)(gate + row * DIN + col), hw = *(const u32x4*)(gate + row * DIN + D + col);
;                 const float ga[8] = {bflo(gw.x), bfhi(gw.x), bflo(gw.y), bfhi(gw.y), bflo(gw.z), bfhi(gw.z), bflo(gw.w), bfhi(gw.w)};
;                 const float gb[8] = {bflo(hw.x), bfhi(hw.x), bflo(hw.y), bfhi(hw.y), bflo(hw.z), bfhi(hw.z), bflo(hw.w), bfhi(hw.w)};
;                 float f[8];
; #pragma unroll
;                 for (int j = 0; j < 8; ++j) f[j] = gb[j] * __builtin_amdgcn_rcpf(ga[j]);
;                 acc[ai][bj][m][0] = acc[ai][bj][m][0] * (f32x4){f[0], f[1], f[2], f[3]}; acc[ai][bj][m][1] = acc[ai][bj][m][1] * (f32x4){f[4], f[5], f[6], f[7]};
;                 asm volatile("" ::: "memory"); } }
	v_lshlrev_b32_e32 v216, 16, v132
	v_and_b32_e32 v217, s12, v132
	v_lshlrev_b32_e32 v218, 16, v133
	v_and_b32_e32 v219, s12, v133
	v_lshlrev_b32_e32 v220, 16, v134
	v_and_b32_e32 v221, s12, v134
	v_lshlrev_b32_e32 v222, 16, v135
	v_and_b32_e32 v223, s12, v135
	v_rcp_f32_e32 v216, v216
	v_rcp_f32_e32 v217, v217
	v_rcp_f32_e32 v218, v218
	v_rcp_f32_e32 v219, v219
	v_rcp_f32_e32 v220, v220
	v_rcp_f32_e32 v221, v221
	v_rcp_f32_e32 v222, v222
	v_rcp_f32_e32 v223, v223
	v_lshlrev_b32_e32 v132, 16, v136
	v_and_b32_e32 v133, s12, v136
	v_lshlrev_b32_e32 v134, 16, v137
	v_and_b32_e32 v135, s12, v137
	v_lshlrev_b32_e32 v136, 16, v138
	v_and_b32_e32 v137, s12, v138
	v_lshlrev_b32_e32 v138, 16, v139
	v_and_b32_e32 v139, s12, v139
	v_pk_mul_f32 v[216:217], v[216:217], v[132:133]
	v_pk_mul_f32 v[218:219], v[218:219], v[134:135]
	v_pk_mul_f32 v[220:221], v[220:221], v[136:137]
	v_pk_mul_f32 v[222:223], v[222:223], v[138:139]
	v_pk_mul_f32 v[68:69], v[68:69], v[216:217]
	v_pk_mul_f32 v[70:71], v[70:71], v[218:219]
	v_pk_mul_f32 v[64:65], v[64:65], v[220:221]
	v_pk_mul_f32 v[66:67], v[66:67], v[222:223]
	global_load_dwordx4 v[132:135], v[82:83], off offset:0
	global_load_dwordx4 v[136:139], v[82:83], off offset:2048
	s_waitcnt vmcnt(12)
	v_lshlrev_b32_e32 v216, 16, v142
	v_and_b32_e32 v217, s12, v142
	v_lshlrev_b32_e32 v218, 16, v143
	v_and_b32_e32 v219, s12, v143
	v_lshlrev_b32_e32 v220, 16, v144
	v_and_b32_e32 v221, s12, v144
	v_lshlrev_b32_e32 v222, 16, v145
	v_and_b32_e32 v223, s12, v145
	v_rcp_f32_e32 v216, v216
	v_rcp_f32_e32 v217, v217
	v_rcp_f32_e32 v218, v218
	v_rcp_f32_e32 v219, v219
	v_rcp_f32_e32 v220, v220
	v_rcp_f32_e32 v221, v221
	v_rcp_f32_e32 v222, v222
	v_rcp_f32_e32 v223, v223
	v_lshlrev_b32_e32 v142, 16, v158
	v_and_b32_e32 v143, s12, v158
	v_lshlrev_b32_e32 v144, 16, v159
	v_and_b32_e32 v145, s12, v159
	v_lshlrev_b32_e32 v158, 16, v160
	v_and_b32_e32 v159, s12, v160
	v_lshlrev_b32_e32 v160, 16, v161
	v_and_b32_e32 v161, s12, v161
	v_pk_mul_f32 v[216:217], v[216:217], v[142:143]
	v_pk_mul_f32 v[218:219], v[218:219], v[144:145]
	v_pk_mul_f32 v[220:221], v[220:221], v[158:159]
	v_pk_mul_f32 v[222:223], v[222:223], v[160:161]
	v_pk_mul_f32 v[60:61], v[60:61], v[216:217]
	v_pk_mul_f32 v[62:63], v[62:63], v[218:219]
	v_pk_mul_f32 v[56:57], v[56:57], v[220:221]
	v_pk_mul_f32 v[58:59], v[58:59], v[222:223]
	global_load_dwordx4 v[142:145], v[82:83], off offset:64
	global_load_dwordx4 v[158:161], v[82:83], off offset:2112
	s_waitcnt vmcnt(12)
	v_lshlrev_b32_e32 v216, 16, v176
	v_and_b32_e32 v217, s12, v176
	v_lshlrev_b32_e32 v218, 16, v177
	v_and_b32_e32 v219, s12, v177
	v_lshlrev_b32_e32 v220, 16, v178
	v_and_b32_e32 v221, s12, v178
	v_lshlrev_b32_e32 v222, 16, v179
	v_and_b32_e32 v223, s12, v179
	v_rcp_f32_e32 v216, v216
	v_rcp_f32_e32 v217, v217
	v_rcp_f32_e32 v218, v218
	v_rcp_f32_e32 v219, v219
	v_rcp_f32_e32 v220, v220
	v_rcp_f32_e32 v221, v221
	v_rcp_f32_e32 v222, v222
	v_rcp_f32_e32 v223, v223
	v_lshlrev_b32_e32 v176, 16, v180
	v_and_b32_e32 v177, s12, v180
	v_lshlrev_b32_e32 v178, 16, v181
	v_and_b32_e32 v179, s12, v181
	v_lshlrev_b32_e32 v180, 16, v182
	v_and_b32_e32 v181, s12, v182
	v_lshlrev_b32_e32 v182, 16, v183
	v_and_b32_e32 v183, s12, v183
	v_pk_mul_f32 v[216:217], v[216:217], v[176:177]
	v_pk_mul_f32 v[218:219], v[218:219], v[178:179]
	v_pk_mul_f32 v[220:221], v[220:221], v[180:181]
	v_pk_mul_f32 v[222:223], v[222:223], v[182:183]
	v_pk_mul_f32 v[52:53], v[52:53], v[216:217]
	v_pk_mul_f32 v[54:55], v[54:55], v[218:219]
	v_pk_mul_f32 v[48:49], v[48:49], v[220:221]
	v_pk_mul_f32 v[50:51], v[50:51], v[222:223]
	s_waitcnt vmcnt(10)
	v_lshlrev_b32_e32 v216, 16, v184
	v_and_b32_e32 v217, s12, v184
	v_lshlrev_b32_e32 v218, 16, v185
	v_and_b32_e32 v219, s12, v185
	v_lshlrev_b32_e32 v220, 16, v186
	v_and_b32_e32 v221, s12, v186
	v_lshlrev_b32_e32 v222, 16, v187
	v_and_b32_e32 v223, s12, v187
	v_rcp_f32_e32 v216, v216
	v_rcp_f32_e32 v217, v217
	v_rcp_f32_e32 v218, v218
	v_rcp_f32_e32 v219, v219
	v_rcp_f32_e32 v220, v220
	v_rcp_f32_e32 v221, v221
	v_rcp_f32_e32 v222, v222
	v_rcp_f32_e32 v223, v223
	v_lshlrev_b32_e32 v184, 16, v188
	v_and_b32_e32 v185, s12, v188
	v_lshlrev_b32_e32 v186, 16, v189
	v_and_b32_e32 v187, s12, v189
	v_lshlrev_b32_e32 v188, 16, v190
	v_and_b32_e32 v189, s12, v190
	v_lshlrev_b32_e32 v190, 16, v191
	v_and_b32_e32 v191, s12, v191
	v_pk_mul_f32 v[216:217], v[216:217], v[184:185]
	v_pk_mul_f32 v[218:219], v[218:219], v[186:187]
	v_pk_mul_f32 v[220:221], v[220:221], v[188:189]
	v_pk_mul_f32 v[222:223], v[222:223], v[190:191]
	v_pk_mul_f32 v[44:45], v[44:45], v[216:217]
	v_pk_mul_f32 v[46:47], v[46:47], v[218:219]
	v_pk_mul_f32 v[40:41], v[40:41], v[220:221]
	v_pk_mul_f32 v[42:43], v[42:43], v[222:223]
	s_waitcnt vmcnt(8)
; DI float bflo(unsigned u) { return __uint_as_float(u << 16); }
; DI float bfhi(unsigned u) { return __uint_as_float(u & 0xffff0000u); }
; DI void merge_carry(f32x4 (&acc)[2][2][4][2], unsigned char* ws, const Unit& u, int z, int wr, int wc, int fr, int fq) {
;     ...
;             for (int bj = 0; bj < 2; ++bj) { const int col = col0 + bj * 32;
;                 const u32x4 gw = *(const u32x4*)(gate + row * DIN + col), hw = *(const u32x4*)(gate + row * DIN + D + col);
;                 const float ga[8] = {bflo(gw.x), bfhi(gw.x), bflo(gw.y), bfhi(gw.y), bflo(gw.z), bfhi(gw.z), bflo(gw.w), bfhi(gw.w)};
;                 const float gb[8] = {bflo(hw.x), bfhi(hw.x), bflo(hw.y), bfhi(hw.y), bflo(hw.z), bfhi(hw.z), bflo(hw.w), bfhi(hw.w)};
;                 float f[8];
; #pragma unroll
;                 for (int j = 0; j < 8; ++j) f[j] = gb[j] * __builtin_amdgcn_rcpf(ga[j]);
;                 acc[ai][bj][m][0] = acc[ai][bj][m][0] * (f32x4){f[0], f[1], f[2], f[3]}; acc[ai][bj][m][1] = acc[ai][bj][m][1] * (f32x4){f[4], f[5], f[6], f[7]};
;                 asm volatile("" ::: "memory"); } }
	v_lshlrev_b32_e32 v216, 16, v192
	v_and_b32_e32 v217, s12, v192
	v_lshlrev_b32_e32 v218, 16, v193
	v_and_b32_e32 v219, s12, v193
	v_lshlrev_b32_e32 v220, 16, v194
	v_and_b32_e32 v221, s12, v194
	v_lshlrev_b32_e32 v222, 16, v195
	v_and_b32_e32 v223, s12, v195
	v_rcp_f32_e32 v216, v216
	v_rcp_f32_e32 v217, v217
	v_rcp_f32_e32 v218, v218
	v_rcp_f32_e32 v219, v219
	v_rcp_f32_e32 v220, v220
	v_rcp_f32_e32 v221, v221
	v_rcp_f32_e32 v222, v222
	v_rcp_f32_e32 v223, v223
	v_lshlrev_b32_e32 v192, 16, v196
	v_and_b32_e32 v193, s12, v196
	v_lshlrev_b32_e32 v194, 16, v197
	v_and_b32_e32 v195, s12, v197
	v_lshlrev_b32_e32 v196, 16, v198
	v_and_b32_e32 v197, s12, v198
	v_lshlrev_b32_e32 v198, 16, v199
	v_and_b32_e32 v199, s12, v199
	v_pk_mul_f32 v[216:217], v[216:217], v[192:193]
	v_pk_mul_f32 v[218:219], v[218:219], v[194:195]
	v_pk_mul_f32 v[220:221], v[220:221], v[196:197]
	v_pk_mul_f32 v[222:223], v[222:223], v[198:199]
	v_pk_mul_f32 v[36:37], v[36:37], v[216:217]
	v_pk_mul_f32 v[38:39], v[38:39], v[218:219]
	v_pk_mul_f32 v[32:33], v[32:33], v[220:221]
	v_pk_mul_f32 v[34:35], v[34:35], v[222:223]
	s_waitcnt vmcnt(6)
	v_lshlrev_b32_e32 v216, 16, v200
	v_and_b32_e32 v217, s12, v200
	v_lshlrev_b32_e32 v218, 16, v201
	v_and_b32_e32 v219, s12, v201
	v_lshlrev_b32_e32 v220, 16, v202
	v_and_b32_e32 v221, s12, v202
	v_lshlrev_b32_e32 v222, 16, v203
	v_and_b32_e32 v223, s12, v203
	v_rcp_f32_e32 v216, v216
	v_rcp_f32_e32 v217, v217
	v_rcp_f32_e32 v218, v218
	v_rcp_f32_e32 v219, v219
	v_rcp_f32_e32 v220, v220
	v_rcp_f32_e32 v221, v221
	v_rcp_f32_e32 v222, v222
	v_rcp_f32_e32 v223, v223
	v_lshlrev_b32_e32 v200, 16, v204
	v_and_b32_e32 v201, s12, v204
	v_lshlrev_b32_e32 v202, 16, v205
	v_and_b32_e32 v203, s12, v205
	v_lshlrev_b32_e32 v204, 16, v206
	v_and_b32_e32 v205, s12, v206
	v_lshlrev_b32_e32 v206, 16, v207
	v_and_b32_e32 v207, s12, v207
	v_pk_mul_f32 v[216:217], v[216:217], v[200:201]
	v_pk_mul_f32 v[218:219], v[218:219], v[202:203]
	v_pk_mul_f32 v[220:221], v[220:221], v[204:205]
	v_pk_mul_f32 v[222:223], v[222:223], v[206:207]
	v_pk_mul_f32 v[28:29], v[28:29], v[216:217]
	v_pk_mul_f32 v[30:31], v[30:31], v[218:219]
	v_pk_mul_f32 v[24:25], v[24:25], v[220:221]
	v_pk_mul_f32 v[26:27], v[26:27], v[222:223]
	s_waitcnt vmcnt(4)
	v_lshlrev_b32_e32 v216, 16, v208
	v_and_b32_e32 v217, s12, v208
	v_lshlrev_b32_e32 v218, 16, v209
	v_and_b32_e32 v219, s12, v209
	v_lshlrev_b32_e32 v220, 16, v210
	v_and_b32_e32 v221, s12, v210
	v_lshlrev_b32_e32 v222, 16, v211
	v_and_b32_e32 v223, s12, v211
	v_rcp_f32_e32 v216, v216
	v_rcp_f32_e32 v217, v217
	v_rcp_f32_e32 v218, v218
	v_rcp_f32_e32 v219, v219
	v_rcp_f32_e32 v220, v220
	v_rcp_f32_e32 v221, v221
	v_rcp_f32_e32 v222, v222
	v_rcp_f32_e32 v223, v223
	v_lshlrev_b32_e32 v208, 16, v212
	v_and_b32_e32 v209, s12, v212
	v_lshlrev_b32_e32 v210, 16, v213
	v_and_b32_e32 v211, s12, v213
	v_lshlrev_b32_e32 v212, 16, v214
	v_and_b32_e32 v213, s12, v214
	v_lshlrev_b32_e32 v214, 16, v215
	v_and_b32_e32 v215, s12, v215
	v_pk_mul_f32 v[216:217], v[216:217], v[208:209]
	v_pk_mul_f32 v[218:219], v[218:219], v[210:211]
	v_pk_mul_f32 v[220:221], v[220:221], v[212:213]
	v_pk_mul_f32 v[222:223], v[222:223], v[214:215]
	v_pk_mul_f32 v[20:21], v[20:21], v[216:217]
	v_pk_mul_f32 v[22:23], v[22:23], v[218:219]
	v_pk_mul_f32 v[16:17], v[16:17], v[220:221]
	v_pk_mul_f32 v[18:19], v[18:19], v[222:223]
	s_waitcnt vmcnt(2)
	v_lshlrev_b32_e32 v216, 16, v132
	v_and_b32_e32 v217, s12, v132
	v_lshlrev_b32_e32 v218, 16, v133
	v_and_b32_e32 v219, s12, v133
	v_lshlrev_b32_e32 v220, 16, v134
	v_and_b32_e32 v221, s12, v134
	v_lshlrev_b32_e32 v222, 16, v135
	v_and_b32_e32 v223, s12, v135
	v_rcp_f32_e32 v216, v216
	v_rcp_f32_e32 v217, v217
	v_rcp_f32_e32 v218, v218
	v_rcp_f32_e32 v219, v219
	v_rcp_f32_e32 v220, v220
	v_rcp_f32_e32 v221, v221
	v_rcp_f32_e32 v222, v222
	v_rcp_f32_e32 v223, v223
	v_lshlrev_b32_e32 v132, 16, v136
	v_and_b32_e32 v133, s12, v136
	v_lshlrev_b32_e32 v134, 16, v137
	v_and_b32_e32 v135, s12, v137
	v_lshlrev_b32_e32 v136, 16, v138
	v_and_b32_e32 v137, s12, v138
	v_lshlrev_b32_e32 v138, 16, v139
	v_and_b32_e32 v139, s12, v139
	v_pk_mul_f32 v[216:217], v[216:217], v[132:133]
	v_pk_mul_f32 v[218:219], v[218:219], v[134:135]
	v_pk_mul_f32 v[220:221], v[220:221], v[136:137]
	v_pk_mul_f32 v[222:223], v[222:223], v[138:139]
	v_pk_mul_f32 v[12:13], v[12:13], v[216:217]
	v_pk_mul_f32 v[14:15], v[14:15], v[218:219]
	v_pk_mul_f32 v[8:9], v[8:9], v[220:221]
	v_pk_mul_f32 v[10:11], v[10:11], v[222:223]
	s_waitcnt vmcnt(0)
	v_lshlrev_b32_e32 v216, 16, v142
	v_and_b32_e32 v217, s12, v142
	v_lshlrev_b32_e32 v218, 16, v143
	v_and_b32_e32 v219, s12, v143
	v_lshlrev_b32_e32 v220, 16, v144
	v_and_b32_e32 v221, s12, v144
	v_lshlrev_b32_e32 v222, 16, v145
	v_and_b32_e32 v223, s12, v145
	v_rcp_f32_e32 v216, v216
	v_rcp_f32_e32 v217, v217
	v_rcp_f32_e32 v218, v218
	v_rcp_f32_e32 v219, v219
	v_rcp_f32_e32 v220, v220
	v_rcp_f32_e32 v221, v221
	v_rcp_f32_e32 v222, v222
	v_rcp_f32_e32 v223, v223
	v_lshlrev_b32_e32 v142, 16, v158
	v_and_b32_e32 v143, s12, v158
	v_lshlrev_b32_e32 v144, 16, v159
	v_and_b32_e32 v145, s12, v159
	v_lshlrev_b32_e32 v158, 16, v160
	v_and_b32_e32 v159, s12, v160
	v_lshlrev_b32_e32 v160, 16, v161
	v_and_b32_e32 v161, s12, v161
	v_pk_mul_f32 v[216:217], v[216:217], v[142:143]
	v_pk_mul_f32 v[218:219], v[218:219], v[144:145]
	v_pk_mul_f32 v[220:221], v[220:221], v[158:159]
	v_pk_mul_f32 v[222:223], v[222:223], v[160:161]
	v_pk_mul_f32 v[4:5], v[4:5], v[216:217]
	v_pk_mul_f32 v[6:7], v[6:7], v[218:219]
	v_pk_mul_f32 v[0:1], v[0:1], v[220:221]
	v_pk_mul_f32 v[2:3], v[2:3], v[222:223]
	s_branch .LBB0_500
